# MFMA order inside each 16-MFMA sub-block: both k-steps of an accumulator back to back (accumulator-chain forwarding), on top of v49
# baseline (speedup 1.0000x reference)
; #define PG8_STAGE(bufoff, gbase, voff) do { _Pragma("unroll") for (int _i = 0; _i < 2; ++_i) \
;         __builtin_amdgcn_global_load_lds((const unsigned*)((const char*)(gbase) + (voff)[_i]), (PG8_LAS unsigned*)(lds + (bufoff) + ldsw + _i * 8192), 16, 0, 0); } while (0)
; #define PG8_LDA(dst, b, h) do { _Pragma("unroll") for (int m = 0; m < 4; ++m) _Pragma("unroll") for (int k = 0; k < 2; ++k) dst[m][k] = *(const PG8_LAS bf16x8*)(lds + PG8_SA(b, h) + aoff + m * 2048 + k * 1024); } while (0)
; #define PG8_WAIT_L(n) asm volatile("s_waitcnt lgkmcnt(" #n ")" ::: "memory")
; #define PG8_WAIT_V_SEL(sel) asm volatile("s_cmp_eq_u32 %0, 0\n\ts_cbranch_scc1 .Lw8_%=\n\ts_waitcnt vmcnt(22)\n\ts_branch .Lwd_%=\n.Lw8_%=:\n\ts_waitcnt vmcnt(8)\n.Lwd_%=:" :: "s"(sel) : "memory", "scc")
; #define PG8_BAR __builtin_amdgcn_s_barrier()
; #define PG8_SCHED __builtin_amdgcn_sched_barrier(0)
;     ...
;             PG8_WAIT_L(0); PG8_BAR; PG8_MMA(0, 0, At, B0); PG8_MMA(0, 1, At, B1); PG8_BAR; PG8_SCHED;
;             PG8_LDA(At, 0, 1); PG8_STAGE(PG8_SB(0, 0), b2, voffB); PG8_STAGE(PG8_SB(0, 1), b2 + hstep, voffB); PG8_STAGE(PG8_SA(0, 0), a2, voffA);
;             PG8_WAIT_V_SEL(relax);
.Lwd_0:
	s_waitcnt lgkmcnt(0)
	s_barrier
	s_setprio 1
	s_waitcnt lgkmcnt(0)
	v_mfma_f32_16x16x32_bf16 v[126:129], v[142:145], v[198:201], v[126:129]
	v_mfma_f32_16x16x32_bf16 v[110:113], v[150:153], v[198:201], v[110:113]
	v_mfma_f32_16x16x32_bf16 v[122:125], v[142:145], v[206:209], v[122:125]
	v_mfma_f32_16x16x32_bf16 v[106:109], v[150:153], v[206:209], v[106:109]
	v_mfma_f32_16x16x32_bf16 v[118:121], v[142:145], v[214:217], v[118:121]
	v_mfma_f32_16x16x32_bf16 v[102:105], v[150:153], v[214:217], v[102:105]
	v_mfma_f32_16x16x32_bf16 v[114:117], v[142:145], v[222:225], v[114:117]
	v_mfma_f32_16x16x32_bf16 v[98:101], v[150:153], v[222:225], v[98:101]
	v_mfma_f32_16x16x32_bf16 v[126:129], v[146:149], v[202:205], v[126:129]
	v_mfma_f32_16x16x32_bf16 v[110:113], v[154:157], v[202:205], v[110:113]
	v_mfma_f32_16x16x32_bf16 v[122:125], v[146:149], v[210:213], v[122:125]
	v_mfma_f32_16x16x32_bf16 v[106:109], v[154:157], v[210:213], v[106:109]
	v_mfma_f32_16x16x32_bf16 v[118:121], v[146:149], v[218:221], v[118:121]
	v_mfma_f32_16x16x32_bf16 v[102:105], v[154:157], v[218:221], v[102:105]
	v_mfma_f32_16x16x32_bf16 v[114:117], v[146:149], v[226:229], v[114:117]
	v_mfma_f32_16x16x32_bf16 v[98:101], v[154:157], v[226:229], v[98:101]
	s_setprio 0
	s_setprio 1
	v_mfma_f32_16x16x32_bf16 v[82:85], v[158:161], v[198:201], v[82:85]
	v_mfma_f32_16x16x32_bf16 v[30:33], v[174:177], v[198:201], v[30:33]
	v_mfma_f32_16x16x32_bf16 v[70:73], v[158:161], v[206:209], v[70:73]
	v_mfma_f32_16x16x32_bf16 v[26:29], v[174:177], v[206:209], v[26:29]
	v_mfma_f32_16x16x32_bf16 v[66:69], v[158:161], v[214:217], v[66:69]
	v_mfma_f32_16x16x32_bf16 v[22:25], v[174:177], v[214:217], v[22:25]
	v_mfma_f32_16x16x32_bf16 v[58:61], v[158:161], v[222:225], v[58:61]
	v_mfma_f32_16x16x32_bf16 v[18:21], v[174:177], v[222:225], v[18:21]
	v_mfma_f32_16x16x32_bf16 v[82:85], v[162:165], v[202:205], v[82:85]
	v_mfma_f32_16x16x32_bf16 v[30:33], v[188:191], v[202:205], v[30:33]
	v_mfma_f32_16x16x32_bf16 v[70:73], v[162:165], v[210:213], v[70:73]
	v_mfma_f32_16x16x32_bf16 v[26:29], v[188:191], v[210:213], v[26:29]
	v_mfma_f32_16x16x32_bf16 v[66:69], v[162:165], v[218:221], v[66:69]
	v_mfma_f32_16x16x32_bf16 v[22:25], v[188:191], v[218:221], v[22:25]
	v_mfma_f32_16x16x32_bf16 v[58:61], v[162:165], v[226:229], v[58:61]
	v_mfma_f32_16x16x32_bf16 v[18:21], v[188:191], v[226:229], v[18:21]
	s_setprio 0
	s_barrier
	s_add_i32 s0, s40, s87
	v_lshl_add_u64 v[168:169], s[80:81], 0, v[182:183]
	s_mov_b32 m0, s0
	ds_read_b128 v[198:201], v196 offset:16384
	ds_read_b128 v[202:205], v196 offset:17408
	ds_read_b128 v[206:209], v196 offset:18432
	ds_read_b128 v[210:213], v196 offset:19456
	ds_read_b128 v[214:217], v196 offset:20480
	ds_read_b128 v[218:221], v196 offset:21504
	ds_read_b128 v[222:225], v196 offset:22528
	ds_read_b128 v[226:229], v196 offset:23552
	global_load_lds_dwordx4 v[168:169], off
	s_add_i32 m0, s0, 0x2000
	s_add_u32 s0, s80, 0x80000
	v_lshl_add_u64 v[184:185], s[80:81], 0, v[134:135]
	s_addc_u32 s1, s81, 0
	s_add_i32 s40, s41, s87
	global_load_lds_dwordx4 v[184:185], off
	v_lshl_add_u64 v[186:187], s[0:1], 0, v[182:183]
	s_mov_b32 m0, s40
	v_lshl_add_u64 v[230:231], s[82:83], 0, v[132:133]
	global_load_lds_dwordx4 v[186:187], off
	v_lshl_add_u64 v[186:187], s[0:1], 0, v[134:135]
	s_add_i32 m0, s40, 0x2000
	s_nop 0
	global_load_lds_dwordx4 v[186:187], off
	v_lshl_add_u64 v[186:187], s[82:83], 0, v[130:131]
	s_mov_b32 m0, s75
	s_nop 0
	global_load_lds_dwordx4 v[186:187], off
	s_mov_b32 m0, s88
	s_nop 0
	global_load_lds_dwordx4 v[230:231], off
	s_cmp_eq_u32 s27, 0
	s_cbranch_scc1 .Lw8_1
	s_waitcnt vmcnt(22)
	s_branch .Lwd_1

; #define PG8_STAGE(bufoff, gbase, voff) do { _Pragma("unroll") for (int _i = 0; _i < 2; ++_i) \
;         __builtin_amdgcn_global_load_lds((const unsigned*)((const char*)(gbase) + (voff)[_i]), (PG8_LAS unsigned*)(lds + (bufoff) + ldsw + _i * 8192), 16, 0, 0); } while (0)
; #define PG8_LDA(dst, b, h) do { _Pragma("unroll") for (int m = 0; m < 4; ++m) _Pragma("unroll") for (int k = 0; k < 2; ++k) dst[m][k] = *(const PG8_LAS bf16x8*)(lds + PG8_SA(b, h) + aoff + m * 2048 + k * 1024); } while (0)
; #define PG8_LDB(dst, b, h) do { _Pragma("unroll") for (int n = 0; n < 2; ++n) _Pragma("unroll") for (int k = 0; k < 2; ++k) dst[n][k] = *(const PG8_LAS bf16x8*)(lds + PG8_SB(b, h) + boff + n * 2048 + k * 1024); } while (0)
; #define PG8_WAIT_V(n) asm volatile("s_waitcnt vmcnt(" #n ")" ::: "memory")
; #define PG8_WAIT_L(n) asm volatile("s_waitcnt lgkmcnt(" #n ")" ::: "memory")
; #define PG8_BAR __builtin_amdgcn_s_barrier()
; #define PG8_SCHED __builtin_amdgcn_sched_barrier(0)
;     ...
;             PG8_WAIT_L(0); PG8_BAR; PG8_MMA(1, 0, At, B0); PG8_MMA(1, 1, At, B1); PG8_BAR; PG8_SCHED;
;             PG8_LDB(B0, 1, 0); PG8_LDB(B1, 1, 1); PG8_SCHED; PG8_LDA(At, 1, 0); PG8_STAGE(PG8_SA(0, 1), a2 + hstep, voffA);
;             PG8_WAIT_V(8); PG8_WAIT_L(0); PG8_BAR; PG8_MMA(0, 0, At, B0); PG8_MMA(0, 1, At, B1); PG8_BAR; PG8_SCHED;
.Lwd_1:
	s_waitcnt lgkmcnt(0)
	s_barrier
	s_setprio 1
	s_waitcnt lgkmcnt(0)
	v_mfma_f32_16x16x32_bf16 v[94:97], v[142:145], v[198:201], v[94:97]
	v_mfma_f32_16x16x32_bf16 v[74:77], v[150:153], v[198:201], v[74:77]
	v_mfma_f32_16x16x32_bf16 v[90:93], v[142:145], v[206:209], v[90:93]
	v_mfma_f32_16x16x32_bf16 v[62:65], v[150:153], v[206:209], v[62:65]
	v_mfma_f32_16x16x32_bf16 v[86:89], v[142:145], v[214:217], v[86:89]
	v_mfma_f32_16x16x32_bf16 v[54:57], v[150:153], v[214:217], v[54:57]
	v_mfma_f32_16x16x32_bf16 v[78:81], v[142:145], v[222:225], v[78:81]
	v_mfma_f32_16x16x32_bf16 v[50:53], v[150:153], v[222:225], v[50:53]
	v_mfma_f32_16x16x32_bf16 v[94:97], v[146:149], v[202:205], v[94:97]
	v_mfma_f32_16x16x32_bf16 v[74:77], v[154:157], v[202:205], v[74:77]
	v_mfma_f32_16x16x32_bf16 v[90:93], v[146:149], v[210:213], v[90:93]
	v_mfma_f32_16x16x32_bf16 v[62:65], v[154:157], v[210:213], v[62:65]
	v_mfma_f32_16x16x32_bf16 v[86:89], v[146:149], v[218:221], v[86:89]
	v_mfma_f32_16x16x32_bf16 v[54:57], v[154:157], v[218:221], v[54:57]
	v_mfma_f32_16x16x32_bf16 v[78:81], v[146:149], v[226:229], v[78:81]
	v_mfma_f32_16x16x32_bf16 v[50:53], v[154:157], v[226:229], v[50:53]
	s_setprio 0
	s_setprio 1
	v_mfma_f32_16x16x32_bf16 v[46:49], v[158:161], v[198:201], v[46:49]
	v_mfma_f32_16x16x32_bf16 v[14:17], v[174:177], v[198:201], v[14:17]
	v_mfma_f32_16x16x32_bf16 v[42:45], v[158:161], v[206:209], v[42:45]
	v_mfma_f32_16x16x32_bf16 v[10:13], v[174:177], v[206:209], v[10:13]
	v_mfma_f32_16x16x32_bf16 v[38:41], v[158:161], v[214:217], v[38:41]
	v_mfma_f32_16x16x32_bf16 v[6:9], v[174:177], v[214:217], v[6:9]
	v_mfma_f32_16x16x32_bf16 v[34:37], v[158:161], v[222:225], v[34:37]
	v_mfma_f32_16x16x32_bf16 v[2:5], v[174:177], v[222:225], v[2:5]
	v_mfma_f32_16x16x32_bf16 v[46:49], v[162:165], v[202:205], v[46:49]
	v_mfma_f32_16x16x32_bf16 v[14:17], v[188:191], v[202:205], v[14:17]
	v_mfma_f32_16x16x32_bf16 v[42:45], v[162:165], v[210:213], v[42:45]
	v_mfma_f32_16x16x32_bf16 v[10:13], v[188:191], v[210:213], v[10:13]
	v_mfma_f32_16x16x32_bf16 v[38:41], v[162:165], v[218:221], v[38:41]
	v_mfma_f32_16x16x32_bf16 v[6:9], v[188:191], v[218:221], v[6:9]
	v_mfma_f32_16x16x32_bf16 v[34:37], v[162:165], v[226:229], v[34:37]
	v_mfma_f32_16x16x32_bf16 v[2:5], v[188:191], v[226:229], v[2:5]
	s_setprio 0
	s_barrier
	s_add_i32 s40, 0, 0x18000
	s_add_i32 s41, 0, 0x1c000
	v_add_u32_e32 v154, s40, v181
	v_add_u32_e32 v166, s41, v181
	ds_read_b128 v[142:145], v154
	ds_read_b128 v[146:149], v154 offset:1024
	ds_read_b128 v[150:153], v154 offset:2048
	ds_read_b128 v[154:157], v154 offset:3072
	ds_read_b128 v[158:161], v166
	ds_read_b128 v[162:165], v166 offset:1024
	ds_read_b128 v[174:177], v166 offset:2048
	ds_read_b128 v[188:191], v166 offset:3072
	s_add_u32 s0, s82, 0x80000
	s_addc_u32 s1, s83, 0
	s_mov_b32 m0, s89
	v_lshl_add_u64 v[236:237], s[0:1], 0, v[130:131]
	ds_read_b128 v[198:201], v196 offset:32768
	ds_read_b128 v[202:205], v196 offset:33792
	ds_read_b128 v[206:209], v196 offset:34816
	ds_read_b128 v[210:213], v196 offset:35840
	ds_read_b128 v[214:217], v196 offset:36864
	ds_read_b128 v[218:221], v196 offset:37888
	ds_read_b128 v[222:225], v196 offset:38912
	ds_read_b128 v[226:229], v196 offset:39936
	global_load_lds_dwordx4 v[236:237], off
	v_lshl_add_u64 v[236:237], s[0:1], 0, v[132:133]
	s_mov_b32 m0, s90
	s_nop 0
	global_load_lds_dwordx4 v[236:237], off
	s_waitcnt vmcnt(8)
	s_waitcnt lgkmcnt(0)
	s_barrier
	s_setprio 1
	s_waitcnt lgkmcnt(0)
	v_mfma_f32_16x16x32_bf16 v[126:129], v[142:145], v[198:201], v[126:129]
	v_mfma_f32_16x16x32_bf16 v[110:113], v[150:153], v[198:201], v[110:113]
	v_mfma_f32_16x16x32_bf16 v[122:125], v[142:145], v[206:209], v[122:125]
	v_mfma_f32_16x16x32_bf16 v[106:109], v[150:153], v[206:209], v[106:109]
	v_mfma_f32_16x16x32_bf16 v[118:121], v[142:145], v[214:217], v[118:121]
	v_mfma_f32_16x16x32_bf16 v[102:105], v[150:153], v[214:217], v[102:105]
	v_mfma_f32_16x16x32_bf16 v[114:117], v[142:145], v[222:225], v[114:117]
	v_mfma_f32_16x16x32_bf16 v[98:101], v[150:153], v[222:225], v[98:101]
	v_mfma_f32_16x16x32_bf16 v[126:129], v[146:149], v[202:205], v[126:129]
	v_mfma_f32_16x16x32_bf16 v[110:113], v[154:157], v[202:205], v[110:113]
	v_mfma_f32_16x16x32_bf16 v[122:125], v[146:149], v[210:213], v[122:125]
	v_mfma_f32_16x16x32_bf16 v[106:109], v[154:157], v[210:213], v[106:109]
	v_mfma_f32_16x16x32_bf16 v[118:121], v[146:149], v[218:221], v[118:121]
	v_mfma_f32_16x16x32_bf16 v[102:105], v[154:157], v[218:221], v[102:105]
	v_mfma_f32_16x16x32_bf16 v[114:117], v[146:149], v[226:229], v[114:117]
	v_mfma_f32_16x16x32_bf16 v[98:101], v[154:157], v[226:229], v[98:101]
	s_setprio 0
	s_setprio 1
	v_mfma_f32_16x16x32_bf16 v[82:85], v[158:161], v[198:201], v[82:85]
	v_mfma_f32_16x16x32_bf16 v[30:33], v[174:177], v[198:201], v[30:33]
	v_mfma_f32_16x16x32_bf16 v[70:73], v[158:161], v[206:209], v[70:73]
	v_mfma_f32_16x16x32_bf16 v[26:29], v[174:177], v[206:209], v[26:29]
	v_mfma_f32_16x16x32_bf16 v[66:69], v[158:161], v[214:217], v[66:69]
	v_mfma_f32_16x16x32_bf16 v[22:25], v[174:177], v[214:217], v[22:25]
	v_mfma_f32_16x16x32_bf16 v[58:61], v[158:161], v[222:225], v[58:61]
	v_mfma_f32_16x16x32_bf16 v[18:21], v[174:177], v[222:225], v[18:21]
	v_mfma_f32_16x16x32_bf16 v[82:85], v[162:165], v[202:205], v[82:85]
	v_mfma_f32_16x16x32_bf16 v[30:33], v[188:191], v[202:205], v[30:33]
	v_mfma_f32_16x16x32_bf16 v[70:73], v[162:165], v[210:213], v[70:73]
	v_mfma_f32_16x16x32_bf16 v[26:29], v[188:191], v[210:213], v[26:29]
	v_mfma_f32_16x16x32_bf16 v[66:69], v[162:165], v[218:221], v[66:69]
	v_mfma_f32_16x16x32_bf16 v[22:25], v[188:191], v[218:221], v[22:25]
	v_mfma_f32_16x16x32_bf16 v[58:61], v[162:165], v[226:229], v[58:61]
	v_mfma_f32_16x16x32_bf16 v[18:21], v[188:191], v[226:229], v[18:21]
	s_setprio 0
	s_barrier
; #define PG8_STAGE(bufoff, gbase, voff) do { _Pragma("unroll") for (int _i = 0; _i < 2; ++_i) \
;         __builtin_amdgcn_global_load_lds((const unsigned*)((const char*)(gbase) + (voff)[_i]), (PG8_LAS unsigned*)(lds + (bufoff) + ldsw + _i * 8192), 16, 0, 0); } while (0)
; #define PG8_LDA(dst, b, h) do { _Pragma("unroll") for (int m = 0; m < 4; ++m) _Pragma("unroll") for (int k = 0; k < 2; ++k) dst[m][k] = *(const PG8_LAS bf16x8*)(lds + PG8_SA(b, h) + aoff + m * 2048 + k * 1024); } while (0)
; #define PG8_WAIT_V(n) asm volatile("s_waitcnt vmcnt(" #n ")" ::: "memory")
; #define PG8_WAIT_L(n) asm volatile("s_waitcnt lgkmcnt(" #n ")" ::: "memory")
; #define PG8_BAR __builtin_amdgcn_s_barrier()
; #define PG8_SCHED __builtin_amdgcn_sched_barrier(0)
;     ...
;             PG8_LDA(At, 1, 1); PG8_STAGE(PG8_SB(1, 0), b3, voffB); PG8_STAGE(PG8_SB(1, 1), b3 + hstep, voffB); PG8_STAGE(PG8_SA(1, 0), a3, voffA);
;             PG8_WAIT_V(8); PG8_WAIT_L(0); PG8_BAR; PG8_MMA(1, 0, At, B0); PG8_MMA(1, 1, At, B1); PG8_BAR; PG8_SCHED;
	s_add_i32 s0, s40, s87
	v_lshl_add_u64 v[168:169], v[168:169], 0, s[28:29]
	s_mov_b32 m0, s0
	ds_read_b128 v[198:201], v196 offset:49152
	ds_read_b128 v[202:205], v196 offset:50176
	ds_read_b128 v[206:209], v196 offset:51200
	ds_read_b128 v[210:213], v196 offset:52224
	ds_read_b128 v[214:217], v196 offset:53248
	ds_read_b128 v[218:221], v196 offset:54272
	ds_read_b128 v[222:225], v196 offset:55296
	ds_read_b128 v[226:229], v196 offset:56320
	global_load_lds_dwordx4 v[168:169], off
	s_add_i32 m0, s0, 0x2000
	s_add_u32 s0, s80, 0x80080
	v_lshl_add_u64 v[168:169], v[184:185], 0, s[28:29]
	s_addc_u32 s1, s81, 0
	s_add_i32 s40, s41, s87
	global_load_lds_dwordx4 v[168:169], off
	v_lshl_add_u64 v[168:169], s[0:1], 0, v[182:183]
	s_mov_b32 m0, s40
	s_nop 0
	global_load_lds_dwordx4 v[168:169], off
	v_lshl_add_u64 v[168:169], s[0:1], 0, v[134:135]
	s_add_i32 m0, s40, 0x2000
	s_nop 0
	global_load_lds_dwordx4 v[168:169], off
	v_lshl_add_u64 v[168:169], v[186:187], 0, s[28:29]
	s_mov_b32 m0, s94
	s_nop 0
	global_load_lds_dwordx4 v[168:169], off
	v_lshl_add_u64 v[168:169], v[230:231], 0, s[28:29]
	s_mov_b32 m0, s95
	s_nop 0
	global_load_lds_dwordx4 v[168:169], off
	s_waitcnt vmcnt(8)
	s_waitcnt lgkmcnt(0)
	s_barrier
	s_setprio 1
	s_waitcnt lgkmcnt(0)
	v_mfma_f32_16x16x32_bf16 v[94:97], v[142:145], v[198:201], v[94:97]
	v_mfma_f32_16x16x32_bf16 v[74:77], v[150:153], v[198:201], v[74:77]
	v_mfma_f32_16x16x32_bf16 v[90:93], v[142:145], v[206:209], v[90:93]
	v_mfma_f32_16x16x32_bf16 v[62:65], v[150:153], v[206:209], v[62:65]
	v_mfma_f32_16x16x32_bf16 v[86:89], v[142:145], v[214:217], v[86:89]
	v_mfma_f32_16x16x32_bf16 v[54:57], v[150:153], v[214:217], v[54:57]
	v_mfma_f32_16x16x32_bf16 v[78:81], v[142:145], v[222:225], v[78:81]
	v_mfma_f32_16x16x32_bf16 v[50:53], v[150:153], v[222:225], v[50:53]
	v_mfma_f32_16x16x32_bf16 v[94:97], v[146:149], v[202:205], v[94:97]
	v_mfma_f32_16x16x32_bf16 v[74:77], v[154:157], v[202:205], v[74:77]
	v_mfma_f32_16x16x32_bf16 v[90:93], v[146:149], v[210:213], v[90:93]
	v_mfma_f32_16x16x32_bf16 v[62:65], v[154:157], v[210:213], v[62:65]
	v_mfma_f32_16x16x32_bf16 v[86:89], v[146:149], v[218:221], v[86:89]
	v_mfma_f32_16x16x32_bf16 v[54:57], v[154:157], v[218:221], v[54:57]
	v_mfma_f32_16x16x32_bf16 v[78:81], v[146:149], v[226:229], v[78:81]
	v_mfma_f32_16x16x32_bf16 v[50:53], v[154:157], v[226:229], v[50:53]
	s_setprio 0
	s_setprio 1
	v_mfma_f32_16x16x32_bf16 v[46:49], v[158:161], v[198:201], v[46:49]
	v_mfma_f32_16x16x32_bf16 v[14:17], v[174:177], v[198:201], v[14:17]
	v_mfma_f32_16x16x32_bf16 v[42:45], v[158:161], v[206:209], v[42:45]
	v_mfma_f32_16x16x32_bf16 v[10:13], v[174:177], v[206:209], v[10:13]
	v_mfma_f32_16x16x32_bf16 v[38:41], v[158:161], v[214:217], v[38:41]
	v_mfma_f32_16x16x32_bf16 v[6:9], v[174:177], v[214:217], v[6:9]
	v_mfma_f32_16x16x32_bf16 v[34:37], v[158:161], v[222:225], v[34:37]
	v_mfma_f32_16x16x32_bf16 v[2:5], v[174:177], v[222:225], v[2:5]
	v_mfma_f32_16x16x32_bf16 v[46:49], v[162:165], v[202:205], v[46:49]
	v_mfma_f32_16x16x32_bf16 v[14:17], v[188:191], v[202:205], v[14:17]
	v_mfma_f32_16x16x32_bf16 v[42:45], v[162:165], v[210:213], v[42:45]
	v_mfma_f32_16x16x32_bf16 v[10:13], v[188:191], v[210:213], v[10:13]
	v_mfma_f32_16x16x32_bf16 v[38:41], v[162:165], v[218:221], v[38:41]
	v_mfma_f32_16x16x32_bf16 v[6:9], v[188:191], v[218:221], v[6:9]
	v_mfma_f32_16x16x32_bf16 v[34:37], v[162:165], v[226:229], v[34:37]
	v_mfma_f32_16x16x32_bf16 v[2:5], v[188:191], v[226:229], v[2:5]
	s_setprio 0
	s_barrier
	s_add_i32 s37, s37, 2
	s_add_u32 s78, s78, 0x100
	s_addc_u32 s79, s79, 0
	s_add_u32 s33, s33, 0x100
	s_addc_u32 s35, s35, 0
	s_cmp_gt_u32 s37, 29
	s_cbranch_scc0 .LBB0_234
	s_and_b64 vcc, exec, s[64:65]
	s_cbranch_vccz .LBB0_237
	s_barrier

; #define PG8_STAGE(bufoff, gbase, voff) do { _Pragma("unroll") for (int _i = 0; _i < 2; ++_i) \
;         __builtin_amdgcn_global_load_lds((const unsigned*)((const char*)(gbase) + (voff)[_i]), (PG8_LAS unsigned*)(lds + (bufoff) + ldsw + _i * 8192), 16, 0, 0); } while (0)
; #define PG8_LDA(dst, b, h) do { _Pragma("unroll") for (int m = 0; m < 4; ++m) _Pragma("unroll") for (int k = 0; k < 2; ++k) dst[m][k] = *(const PG8_LAS bf16x8*)(lds + PG8_SA(b, h) + aoff + m * 2048 + k * 1024); } while (0)
; #define PG8_WAIT_L(n) asm volatile("s_waitcnt lgkmcnt(" #n ")" ::: "memory")
; #define PG8_WAIT_V_SEL(sel) asm volatile("s_cmp_eq_u32 %0, 0\n\ts_cbranch_scc1 .Lw8_%=\n\ts_waitcnt vmcnt(22)\n\ts_branch .Lwd_%=\n.Lw8_%=:\n\ts_waitcnt vmcnt(8)\n.Lwd_%=:" :: "s"(sel) : "memory", "scc")
; #define PG8_BAR __builtin_amdgcn_s_barrier()
; #define PG8_SCHED __builtin_amdgcn_sched_barrier(0)
;     ...
;             PG8_WAIT_L(0); PG8_BAR; PG8_MMA(0, 0, At, B0); PG8_MMA(0, 1, At, B1); PG8_BAR; PG8_SCHED;
;             PG8_LDA(At, 0, 1); PG8_STAGE(PG8_SB(0, 0), b2, voffB); PG8_STAGE(PG8_SB(0, 1), b2 + hstep, voffB); PG8_STAGE(PG8_SA(0, 0), a2, voffA);
;             PG8_WAIT_V_SEL(relax);
.Lwd_2:
	s_waitcnt lgkmcnt(0)
	s_barrier
	s_setprio 1
	s_waitcnt lgkmcnt(0)
	v_mfma_f32_16x16x32_bf16 v[142:145], v[90:93], v[162:165], v[142:145]
	v_mfma_f32_16x16x32_bf16 v[138:141], v[98:101], v[162:165], v[138:141]
	v_mfma_f32_16x16x32_bf16 v[126:129], v[90:93], v[184:187], v[126:129]
	v_mfma_f32_16x16x32_bf16 v[122:125], v[98:101], v[184:187], v[122:125]
	v_mfma_f32_16x16x32_bf16 v[110:113], v[90:93], v[194:197], v[110:113]
	v_mfma_f32_16x16x32_bf16 v[106:109], v[98:101], v[194:197], v[106:109]
	v_mfma_f32_16x16x32_bf16 v[78:81], v[90:93], v[202:205], v[78:81]
	v_mfma_f32_16x16x32_bf16 v[74:77], v[98:101], v[202:205], v[74:77]
	v_mfma_f32_16x16x32_bf16 v[142:145], v[94:97], v[166:169], v[142:145]
	v_mfma_f32_16x16x32_bf16 v[138:141], v[102:105], v[166:169], v[138:141]
	v_mfma_f32_16x16x32_bf16 v[126:129], v[94:97], v[190:193], v[126:129]
	v_mfma_f32_16x16x32_bf16 v[122:125], v[102:105], v[190:193], v[122:125]
	v_mfma_f32_16x16x32_bf16 v[110:113], v[94:97], v[198:201], v[110:113]
	v_mfma_f32_16x16x32_bf16 v[106:109], v[102:105], v[198:201], v[106:109]
	v_mfma_f32_16x16x32_bf16 v[78:81], v[94:97], v[206:209], v[78:81]
	v_mfma_f32_16x16x32_bf16 v[74:77], v[102:105], v[206:209], v[74:77]
	s_setprio 0
	s_setprio 1
	v_mfma_f32_16x16x32_bf16 v[134:137], v[146:149], v[162:165], v[134:137]
	v_mfma_f32_16x16x32_bf16 v[130:133], v[154:157], v[162:165], v[130:133]
	v_mfma_f32_16x16x32_bf16 v[118:121], v[146:149], v[184:187], v[118:121]
	v_mfma_f32_16x16x32_bf16 v[114:117], v[154:157], v[184:187], v[114:117]
	v_mfma_f32_16x16x32_bf16 v[86:89], v[146:149], v[194:197], v[86:89]
	v_mfma_f32_16x16x32_bf16 v[82:85], v[154:157], v[194:197], v[82:85]
	v_mfma_f32_16x16x32_bf16 v[70:73], v[146:149], v[202:205], v[70:73]
	v_mfma_f32_16x16x32_bf16 v[66:69], v[154:157], v[202:205], v[66:69]
	v_mfma_f32_16x16x32_bf16 v[134:137], v[150:153], v[166:169], v[134:137]
	v_mfma_f32_16x16x32_bf16 v[130:133], v[158:161], v[166:169], v[130:133]
	v_mfma_f32_16x16x32_bf16 v[118:121], v[150:153], v[190:193], v[118:121]
	v_mfma_f32_16x16x32_bf16 v[114:117], v[158:161], v[190:193], v[114:117]
	v_mfma_f32_16x16x32_bf16 v[86:89], v[150:153], v[198:201], v[86:89]
	v_mfma_f32_16x16x32_bf16 v[82:85], v[158:161], v[198:201], v[82:85]
	v_mfma_f32_16x16x32_bf16 v[70:73], v[150:153], v[206:209], v[70:73]
	v_mfma_f32_16x16x32_bf16 v[66:69], v[158:161], v[206:209], v[66:69]
	s_setprio 0
	s_barrier
	s_add_i32 s0, s79, s30
	v_lshl_add_u64 v[210:211], s[84:85], 0, v[182:183]
	s_mov_b32 m0, s0
	ds_read_b128 v[162:165], v230 offset:16384
	ds_read_b128 v[166:169], v230 offset:17408
	ds_read_b128 v[184:187], v230 offset:18432
	ds_read_b128 v[190:193], v230 offset:19456
	ds_read_b128 v[194:197], v230 offset:20480
	ds_read_b128 v[198:201], v230 offset:21504
	ds_read_b128 v[202:205], v230 offset:22528
	ds_read_b128 v[206:209], v230 offset:23552
	global_load_lds_dwordx4 v[210:211], off
	s_add_i32 m0, s0, 0x2000
	s_add_u32 s0, s84, 0x80000
	v_lshl_add_u64 v[212:213], s[84:85], 0, v[178:179]
	s_addc_u32 s1, s85, 0
	s_add_i32 s79, s81, s30
	global_load_lds_dwordx4 v[212:213], off
	v_lshl_add_u64 v[214:215], s[0:1], 0, v[182:183]
	s_mov_b32 m0, s79
	v_lshl_add_u64 v[216:217], s[86:87], 0, v[176:177]
	global_load_lds_dwordx4 v[214:215], off
	v_lshl_add_u64 v[214:215], s[0:1], 0, v[178:179]
	s_add_i32 m0, s79, 0x2000
	s_nop 0
	global_load_lds_dwordx4 v[214:215], off
	v_lshl_add_u64 v[214:215], s[86:87], 0, v[174:175]
	s_mov_b32 m0, s44
	s_nop 0
	global_load_lds_dwordx4 v[214:215], off
	s_mov_b32 m0, s45
	s_nop 0
	global_load_lds_dwordx4 v[216:217], off
	s_cmp_eq_u32 s27, 0
	s_cbranch_scc1 .Lw8_3
	s_waitcnt vmcnt(22)
	s_branch .Lwd_3

; #define PG8_STAGE(bufoff, gbase, voff) do { _Pragma("unroll") for (int _i = 0; _i < 2; ++_i) \
;         __builtin_amdgcn_global_load_lds((const unsigned*)((const char*)(gbase) + (voff)[_i]), (PG8_LAS unsigned*)(lds + (bufoff) + ldsw + _i * 8192), 16, 0, 0); } while (0)
; #define PG8_LDA(dst, b, h) do { _Pragma("unroll") for (int m = 0; m < 4; ++m) _Pragma("unroll") for (int k = 0; k < 2; ++k) dst[m][k] = *(const PG8_LAS bf16x8*)(lds + PG8_SA(b, h) + aoff + m * 2048 + k * 1024); } while (0)
; #define PG8_LDB(dst, b, h) do { _Pragma("unroll") for (int n = 0; n < 2; ++n) _Pragma("unroll") for (int k = 0; k < 2; ++k) dst[n][k] = *(const PG8_LAS bf16x8*)(lds + PG8_SB(b, h) + boff + n * 2048 + k * 1024); } while (0)
; #define PG8_WAIT_V(n) asm volatile("s_waitcnt vmcnt(" #n ")" ::: "memory")
; #define PG8_WAIT_L(n) asm volatile("s_waitcnt lgkmcnt(" #n ")" ::: "memory")
; #define PG8_BAR __builtin_amdgcn_s_barrier()
; #define PG8_SCHED __builtin_amdgcn_sched_barrier(0)
;     ...
;             PG8_WAIT_L(0); PG8_BAR; PG8_MMA(1, 0, At, B0); PG8_MMA(1, 1, At, B1); PG8_BAR; PG8_SCHED;
;             PG8_LDB(B0, 1, 0); PG8_LDB(B1, 1, 1); PG8_SCHED; PG8_LDA(At, 1, 0); PG8_STAGE(PG8_SA(0, 1), a2 + hstep, voffA);
;             PG8_WAIT_V(8); PG8_WAIT_L(0); PG8_BAR; PG8_MMA(0, 0, At, B0); PG8_MMA(0, 1, At, B1); PG8_BAR; PG8_SCHED;
.Lwd_3:
	s_waitcnt lgkmcnt(0)
	s_barrier
	s_setprio 1
	s_waitcnt lgkmcnt(0)
	v_mfma_f32_16x16x32_bf16 v[62:65], v[90:93], v[162:165], v[62:65]
	v_mfma_f32_16x16x32_bf16 v[58:61], v[98:101], v[162:165], v[58:61]
	v_mfma_f32_16x16x32_bf16 v[46:49], v[90:93], v[184:187], v[46:49]
	v_mfma_f32_16x16x32_bf16 v[42:45], v[98:101], v[184:187], v[42:45]
	v_mfma_f32_16x16x32_bf16 v[30:33], v[90:93], v[194:197], v[30:33]
	v_mfma_f32_16x16x32_bf16 v[26:29], v[98:101], v[194:197], v[26:29]
	v_mfma_f32_16x16x32_bf16 v[14:17], v[90:93], v[202:205], v[14:17]
	v_mfma_f32_16x16x32_bf16 v[10:13], v[98:101], v[202:205], v[10:13]
	v_mfma_f32_16x16x32_bf16 v[62:65], v[94:97], v[166:169], v[62:65]
	v_mfma_f32_16x16x32_bf16 v[58:61], v[102:105], v[166:169], v[58:61]
	v_mfma_f32_16x16x32_bf16 v[46:49], v[94:97], v[190:193], v[46:49]
	v_mfma_f32_16x16x32_bf16 v[42:45], v[102:105], v[190:193], v[42:45]
	v_mfma_f32_16x16x32_bf16 v[30:33], v[94:97], v[198:201], v[30:33]
	v_mfma_f32_16x16x32_bf16 v[26:29], v[102:105], v[198:201], v[26:29]
	v_mfma_f32_16x16x32_bf16 v[14:17], v[94:97], v[206:209], v[14:17]
	v_mfma_f32_16x16x32_bf16 v[10:13], v[102:105], v[206:209], v[10:13]
	s_setprio 0
	s_setprio 1
	v_mfma_f32_16x16x32_bf16 v[54:57], v[146:149], v[162:165], v[54:57]
	v_mfma_f32_16x16x32_bf16 v[50:53], v[154:157], v[162:165], v[50:53]
	v_mfma_f32_16x16x32_bf16 v[38:41], v[146:149], v[184:187], v[38:41]
	v_mfma_f32_16x16x32_bf16 v[34:37], v[154:157], v[184:187], v[34:37]
	v_mfma_f32_16x16x32_bf16 v[22:25], v[146:149], v[194:197], v[22:25]
	v_mfma_f32_16x16x32_bf16 v[18:21], v[154:157], v[194:197], v[18:21]
	v_mfma_f32_16x16x32_bf16 v[6:9], v[146:149], v[202:205], v[6:9]
	v_mfma_f32_16x16x32_bf16 v[2:5], v[154:157], v[202:205], v[2:5]
	v_mfma_f32_16x16x32_bf16 v[54:57], v[150:153], v[166:169], v[54:57]
	v_mfma_f32_16x16x32_bf16 v[50:53], v[158:161], v[166:169], v[50:53]
	v_mfma_f32_16x16x32_bf16 v[38:41], v[150:153], v[190:193], v[38:41]
	v_mfma_f32_16x16x32_bf16 v[34:37], v[158:161], v[190:193], v[34:37]
	v_mfma_f32_16x16x32_bf16 v[22:25], v[150:153], v[198:201], v[22:25]
	v_mfma_f32_16x16x32_bf16 v[18:21], v[158:161], v[198:201], v[18:21]
	v_mfma_f32_16x16x32_bf16 v[6:9], v[150:153], v[206:209], v[6:9]
	v_mfma_f32_16x16x32_bf16 v[2:5], v[158:161], v[206:209], v[2:5]
	s_setprio 0
	s_barrier
	s_add_i32 s79, 0, 0x18000
	s_add_i32 s81, 0, 0x1c000
	v_add_u32_e32 v102, s79, v227
	v_add_u32_e32 v158, s81, v227
	ds_read_b128 v[90:93], v102
	ds_read_b128 v[94:97], v102 offset:1024
	ds_read_b128 v[98:101], v102 offset:2048
	ds_read_b128 v[102:105], v102 offset:3072
	ds_read_b128 v[146:149], v158
	ds_read_b128 v[150:153], v158 offset:1024
	ds_read_b128 v[154:157], v158 offset:2048
	ds_read_b128 v[158:161], v158 offset:3072
	s_add_u32 s0, s86, 0x80000
	s_addc_u32 s1, s87, 0
	s_mov_b32 m0, s46
	v_lshl_add_u64 v[218:219], s[0:1], 0, v[174:175]
	ds_read_b128 v[162:165], v230 offset:32768
	ds_read_b128 v[166:169], v230 offset:33792
	ds_read_b128 v[184:187], v230 offset:34816
	ds_read_b128 v[190:193], v230 offset:35840
	ds_read_b128 v[194:197], v230 offset:36864
	ds_read_b128 v[198:201], v230 offset:37888
	ds_read_b128 v[202:205], v230 offset:38912
	ds_read_b128 v[206:209], v230 offset:39936
	global_load_lds_dwordx4 v[218:219], off
	v_lshl_add_u64 v[218:219], s[0:1], 0, v[176:177]
	s_mov_b32 m0, s47
	s_nop 0
	global_load_lds_dwordx4 v[218:219], off
	s_waitcnt vmcnt(8)
	s_waitcnt lgkmcnt(0)
	s_barrier
	s_setprio 1
	s_waitcnt lgkmcnt(0)
	v_mfma_f32_16x16x32_bf16 v[142:145], v[90:93], v[162:165], v[142:145]
	v_mfma_f32_16x16x32_bf16 v[138:141], v[98:101], v[162:165], v[138:141]
	v_mfma_f32_16x16x32_bf16 v[126:129], v[90:93], v[184:187], v[126:129]
	v_mfma_f32_16x16x32_bf16 v[122:125], v[98:101], v[184:187], v[122:125]
	v_mfma_f32_16x16x32_bf16 v[110:113], v[90:93], v[194:197], v[110:113]
	v_mfma_f32_16x16x32_bf16 v[106:109], v[98:101], v[194:197], v[106:109]
	v_mfma_f32_16x16x32_bf16 v[78:81], v[90:93], v[202:205], v[78:81]
	v_mfma_f32_16x16x32_bf16 v[74:77], v[98:101], v[202:205], v[74:77]
	v_mfma_f32_16x16x32_bf16 v[142:145], v[94:97], v[166:169], v[142:145]
	v_mfma_f32_16x16x32_bf16 v[138:141], v[102:105], v[166:169], v[138:141]
	v_mfma_f32_16x16x32_bf16 v[126:129], v[94:97], v[190:193], v[126:129]
	v_mfma_f32_16x16x32_bf16 v[122:125], v[102:105], v[190:193], v[122:125]
	v_mfma_f32_16x16x32_bf16 v[110:113], v[94:97], v[198:201], v[110:113]
	v_mfma_f32_16x16x32_bf16 v[106:109], v[102:105], v[198:201], v[106:109]
	v_mfma_f32_16x16x32_bf16 v[78:81], v[94:97], v[206:209], v[78:81]
	v_mfma_f32_16x16x32_bf16 v[74:77], v[102:105], v[206:209], v[74:77]
	s_setprio 0
	s_setprio 1
	v_mfma_f32_16x16x32_bf16 v[134:137], v[146:149], v[162:165], v[134:137]
	v_mfma_f32_16x16x32_bf16 v[130:133], v[154:157], v[162:165], v[130:133]
	v_mfma_f32_16x16x32_bf16 v[118:121], v[146:149], v[184:187], v[118:121]
	v_mfma_f32_16x16x32_bf16 v[114:117], v[154:157], v[184:187], v[114:117]
	v_mfma_f32_16x16x32_bf16 v[86:89], v[146:149], v[194:197], v[86:89]
	v_mfma_f32_16x16x32_bf16 v[82:85], v[154:157], v[194:197], v[82:85]
	v_mfma_f32_16x16x32_bf16 v[70:73], v[146:149], v[202:205], v[70:73]
	v_mfma_f32_16x16x32_bf16 v[66:69], v[154:157], v[202:205], v[66:69]
	v_mfma_f32_16x16x32_bf16 v[134:137], v[150:153], v[166:169], v[134:137]
	v_mfma_f32_16x16x32_bf16 v[130:133], v[158:161], v[166:169], v[130:133]
	v_mfma_f32_16x16x32_bf16 v[118:121], v[150:153], v[190:193], v[118:121]
	v_mfma_f32_16x16x32_bf16 v[114:117], v[158:161], v[190:193], v[114:117]
	v_mfma_f32_16x16x32_bf16 v[86:89], v[150:153], v[198:201], v[86:89]
	v_mfma_f32_16x16x32_bf16 v[82:85], v[158:161], v[198:201], v[82:85]
	v_mfma_f32_16x16x32_bf16 v[70:73], v[150:153], v[206:209], v[70:73]
	v_mfma_f32_16x16x32_bf16 v[66:69], v[158:161], v[206:209], v[66:69]
	s_setprio 0
	s_barrier
; #define PG8_STAGE(bufoff, gbase, voff) do { _Pragma("unroll") for (int _i = 0; _i < 2; ++_i) \
;         __builtin_amdgcn_global_load_lds((const unsigned*)((const char*)(gbase) + (voff)[_i]), (PG8_LAS unsigned*)(lds + (bufoff) + ldsw + _i * 8192), 16, 0, 0); } while (0)
; #define PG8_LDA(dst, b, h) do { _Pragma("unroll") for (int m = 0; m < 4; ++m) _Pragma("unroll") for (int k = 0; k < 2; ++k) dst[m][k] = *(const PG8_LAS bf16x8*)(lds + PG8_SA(b, h) + aoff + m * 2048 + k * 1024); } while (0)
; #define PG8_WAIT_V(n) asm volatile("s_waitcnt vmcnt(" #n ")" ::: "memory")
; #define PG8_WAIT_L(n) asm volatile("s_waitcnt lgkmcnt(" #n ")" ::: "memory")
; #define PG8_BAR __builtin_amdgcn_s_barrier()
; #define PG8_SCHED __builtin_amdgcn_sched_barrier(0)
;     ...
;             PG8_LDA(At, 1, 1); PG8_STAGE(PG8_SB(1, 0), b3, voffB); PG8_STAGE(PG8_SB(1, 1), b3 + hstep, voffB); PG8_STAGE(PG8_SA(1, 0), a3, voffA);
;             PG8_WAIT_V(8); PG8_WAIT_L(0); PG8_BAR; PG8_MMA(1, 0, At, B0); PG8_MMA(1, 1, At, B1); PG8_BAR; PG8_SCHED;
	s_add_i32 s0, s79, s30
	v_lshl_add_u64 v[210:211], v[210:211], 0, s[28:29]
	s_mov_b32 m0, s0
	ds_read_b128 v[162:165], v230 offset:49152
	ds_read_b128 v[166:169], v230 offset:50176
	ds_read_b128 v[184:187], v230 offset:51200
	ds_read_b128 v[190:193], v230 offset:52224
	ds_read_b128 v[194:197], v230 offset:53248
	ds_read_b128 v[198:201], v230 offset:54272
	ds_read_b128 v[202:205], v230 offset:55296
	ds_read_b128 v[206:209], v230 offset:56320
	global_load_lds_dwordx4 v[210:211], off
	s_add_i32 m0, s0, 0x2000
	s_add_u32 s0, s84, 0x80080
	v_lshl_add_u64 v[210:211], v[212:213], 0, s[28:29]
	s_addc_u32 s1, s85, 0
	s_add_i32 s79, s81, s30
	global_load_lds_dwordx4 v[210:211], off
	v_lshl_add_u64 v[210:211], s[0:1], 0, v[182:183]
	s_mov_b32 m0, s79
	s_nop 0
	global_load_lds_dwordx4 v[210:211], off
	v_lshl_add_u64 v[210:211], s[0:1], 0, v[178:179]
	s_add_i32 m0, s79, 0x2000
	s_nop 0
	global_load_lds_dwordx4 v[210:211], off
	v_lshl_add_u64 v[210:211], v[214:215], 0, s[28:29]
	s_mov_b32 m0, s49
	s_nop 0
	global_load_lds_dwordx4 v[210:211], off
	v_lshl_add_u64 v[210:211], v[216:217], 0, s[28:29]
	s_mov_b32 m0, s50
	s_nop 0
	global_load_lds_dwordx4 v[210:211], off
	s_waitcnt vmcnt(8)
	s_waitcnt lgkmcnt(0)
	s_barrier
	s_setprio 1
	s_waitcnt lgkmcnt(0)
	v_mfma_f32_16x16x32_bf16 v[62:65], v[90:93], v[162:165], v[62:65]
	v_mfma_f32_16x16x32_bf16 v[58:61], v[98:101], v[162:165], v[58:61]
	v_mfma_f32_16x16x32_bf16 v[46:49], v[90:93], v[184:187], v[46:49]
	v_mfma_f32_16x16x32_bf16 v[42:45], v[98:101], v[184:187], v[42:45]
	v_mfma_f32_16x16x32_bf16 v[30:33], v[90:93], v[194:197], v[30:33]
	v_mfma_f32_16x16x32_bf16 v[26:29], v[98:101], v[194:197], v[26:29]
	v_mfma_f32_16x16x32_bf16 v[14:17], v[90:93], v[202:205], v[14:17]
	v_mfma_f32_16x16x32_bf16 v[10:13], v[98:101], v[202:205], v[10:13]
	v_mfma_f32_16x16x32_bf16 v[62:65], v[94:97], v[166:169], v[62:65]
	v_mfma_f32_16x16x32_bf16 v[58:61], v[102:105], v[166:169], v[58:61]
	v_mfma_f32_16x16x32_bf16 v[46:49], v[94:97], v[190:193], v[46:49]
	v_mfma_f32_16x16x32_bf16 v[42:45], v[102:105], v[190:193], v[42:45]
	v_mfma_f32_16x16x32_bf16 v[30:33], v[94:97], v[198:201], v[30:33]
	v_mfma_f32_16x16x32_bf16 v[26:29], v[102:105], v[198:201], v[26:29]
	v_mfma_f32_16x16x32_bf16 v[14:17], v[94:97], v[206:209], v[14:17]
	v_mfma_f32_16x16x32_bf16 v[10:13], v[102:105], v[206:209], v[10:13]
	s_setprio 0
	s_setprio 1
	v_mfma_f32_16x16x32_bf16 v[54:57], v[146:149], v[162:165], v[54:57]
	v_mfma_f32_16x16x32_bf16 v[50:53], v[154:157], v[162:165], v[50:53]
	v_mfma_f32_16x16x32_bf16 v[38:41], v[146:149], v[184:187], v[38:41]
	v_mfma_f32_16x16x32_bf16 v[34:37], v[154:157], v[184:187], v[34:37]
	v_mfma_f32_16x16x32_bf16 v[22:25], v[146:149], v[194:197], v[22:25]
	v_mfma_f32_16x16x32_bf16 v[18:21], v[154:157], v[194:197], v[18:21]
	v_mfma_f32_16x16x32_bf16 v[6:9], v[146:149], v[202:205], v[6:9]
	v_mfma_f32_16x16x32_bf16 v[2:5], v[154:157], v[202:205], v[2:5]
	v_mfma_f32_16x16x32_bf16 v[54:57], v[150:153], v[166:169], v[54:57]
	v_mfma_f32_16x16x32_bf16 v[50:53], v[158:161], v[166:169], v[50:53]
	v_mfma_f32_16x16x32_bf16 v[38:41], v[150:153], v[190:193], v[38:41]
	v_mfma_f32_16x16x32_bf16 v[34:37], v[158:161], v[190:193], v[34:37]
	v_mfma_f32_16x16x32_bf16 v[22:25], v[150:153], v[198:201], v[22:25]
	v_mfma_f32_16x16x32_bf16 v[18:21], v[158:161], v[198:201], v[18:21]
	v_mfma_f32_16x16x32_bf16 v[6:9], v[150:153], v[206:209], v[6:9]
	v_mfma_f32_16x16x32_bf16 v[2:5], v[158:161], v[206:209], v[2:5]
	s_setprio 0
	s_barrier
	s_add_i32 s73, s73, 2
	s_add_u32 s82, s82, 0x100
	s_addc_u32 s83, s83, 0
	s_add_u32 s59, s59, 0x100
	s_addc_u32 s71, s71, 0
	s_cmp_gt_u32 s73, 29
	s_cbranch_scc0 .LBB0_541
	s_and_b64 vcc, exec, s[68:69]
	s_cbranch_vccz .LBB0_544
	s_barrier

; #define PG8_STAGE(bufoff, gbase, voff) do { _Pragma("unroll") for (int _i = 0; _i < 2; ++_i) \
;         __builtin_amdgcn_global_load_lds((const unsigned*)((const char*)(gbase) + (voff)[_i]), (PG8_LAS unsigned*)(lds + (bufoff) + ldsw + _i * 8192), 16, 0, 0); } while (0)
; #define PG8_LDA(dst, b, h) do { _Pragma("unroll") for (int m = 0; m < 4; ++m) _Pragma("unroll") for (int k = 0; k < 2; ++k) dst[m][k] = *(const PG8_LAS bf16x8*)(lds + PG8_SA(b, h) + aoff + m * 2048 + k * 1024); } while (0)
; #define PG8_WAIT_L(n) asm volatile("s_waitcnt lgkmcnt(" #n ")" ::: "memory")
; #define PG8_WAIT_V_SEL(sel) asm volatile("s_cmp_eq_u32 %0, 0\n\ts_cbranch_scc1 .Lw8_%=\n\ts_waitcnt vmcnt(22)\n\ts_branch .Lwd_%=\n.Lw8_%=:\n\ts_waitcnt vmcnt(8)\n.Lwd_%=:" :: "s"(sel) : "memory", "scc")
; #define PG8_BAR __builtin_amdgcn_s_barrier()
; #define PG8_SCHED __builtin_amdgcn_sched_barrier(0)
;     ...
;             PG8_WAIT_L(0); PG8_BAR; PG8_MMA(0, 0, At, B0); PG8_MMA(0, 1, At, B1); PG8_BAR; PG8_SCHED;
;             PG8_LDA(At, 0, 1); PG8_STAGE(PG8_SB(0, 0), b2, voffB); PG8_STAGE(PG8_SB(0, 1), b2 + hstep, voffB); PG8_STAGE(PG8_SA(0, 0), a2, voffA);
;             PG8_WAIT_V_SEL(relax);
.Lwd_4:
	s_waitcnt lgkmcnt(0)
	s_barrier
	s_setprio 1
	s_waitcnt lgkmcnt(0)
	v_mfma_f32_16x16x32_bf16 v[126:129], v[150:153], v[192:195], v[126:129]
	v_mfma_f32_16x16x32_bf16 v[110:113], v[158:161], v[192:195], v[110:113]
	v_mfma_f32_16x16x32_bf16 v[122:125], v[150:153], v[200:203], v[122:125]
	v_mfma_f32_16x16x32_bf16 v[106:109], v[158:161], v[200:203], v[106:109]
	v_mfma_f32_16x16x32_bf16 v[118:121], v[150:153], v[208:211], v[118:121]
	v_mfma_f32_16x16x32_bf16 v[102:105], v[158:161], v[208:211], v[102:105]
	v_mfma_f32_16x16x32_bf16 v[114:117], v[150:153], v[216:219], v[114:117]
	v_mfma_f32_16x16x32_bf16 v[98:101], v[158:161], v[216:219], v[98:101]
	v_mfma_f32_16x16x32_bf16 v[126:129], v[154:157], v[196:199], v[126:129]
	v_mfma_f32_16x16x32_bf16 v[110:113], v[162:165], v[196:199], v[110:113]
	v_mfma_f32_16x16x32_bf16 v[122:125], v[154:157], v[204:207], v[122:125]
	v_mfma_f32_16x16x32_bf16 v[106:109], v[162:165], v[204:207], v[106:109]
	v_mfma_f32_16x16x32_bf16 v[118:121], v[154:157], v[212:215], v[118:121]
	v_mfma_f32_16x16x32_bf16 v[102:105], v[162:165], v[212:215], v[102:105]
	v_mfma_f32_16x16x32_bf16 v[114:117], v[154:157], v[220:223], v[114:117]
	v_mfma_f32_16x16x32_bf16 v[98:101], v[162:165], v[220:223], v[98:101]
	s_setprio 0
	s_setprio 1
	v_mfma_f32_16x16x32_bf16 v[70:73], v[166:169], v[192:195], v[70:73]
	v_mfma_f32_16x16x32_bf16 v[50:53], v[176:179], v[192:195], v[50:53]
	v_mfma_f32_16x16x32_bf16 v[66:69], v[166:169], v[200:203], v[66:69]
	v_mfma_f32_16x16x32_bf16 v[42:45], v[176:179], v[200:203], v[42:45]
	v_mfma_f32_16x16x32_bf16 v[58:61], v[166:169], v[208:211], v[58:61]
	v_mfma_f32_16x16x32_bf16 v[38:41], v[176:179], v[208:211], v[38:41]
	v_mfma_f32_16x16x32_bf16 v[46:49], v[166:169], v[216:219], v[46:49]
	v_mfma_f32_16x16x32_bf16 v[34:37], v[176:179], v[216:219], v[34:37]
	v_mfma_f32_16x16x32_bf16 v[70:73], v[172:175], v[196:199], v[70:73]
	v_mfma_f32_16x16x32_bf16 v[50:53], v[188:191], v[196:199], v[50:53]
	v_mfma_f32_16x16x32_bf16 v[66:69], v[172:175], v[204:207], v[66:69]
	v_mfma_f32_16x16x32_bf16 v[42:45], v[188:191], v[204:207], v[42:45]
	v_mfma_f32_16x16x32_bf16 v[58:61], v[172:175], v[212:215], v[58:61]
	v_mfma_f32_16x16x32_bf16 v[38:41], v[188:191], v[212:215], v[38:41]
	v_mfma_f32_16x16x32_bf16 v[46:49], v[172:175], v[220:223], v[46:49]
	v_mfma_f32_16x16x32_bf16 v[34:37], v[188:191], v[220:223], v[34:37]
	s_setprio 0
	s_barrier
	s_add_i32 s0, s83, s20
	v_lshl_add_u64 v[180:181], s[76:77], 0, v[132:133]
	s_mov_b32 m0, s0
	ds_read_b128 v[192:195], v148 offset:16384
	ds_read_b128 v[196:199], v148 offset:17408
	ds_read_b128 v[200:203], v148 offset:18432
	ds_read_b128 v[204:207], v148 offset:19456
	ds_read_b128 v[208:211], v148 offset:20480
	ds_read_b128 v[212:215], v148 offset:21504
	ds_read_b128 v[216:219], v148 offset:22528
	ds_read_b128 v[220:223], v148 offset:23552
	global_load_lds_dwordx4 v[180:181], off
	s_add_i32 m0, s0, 0x2000
	s_add_u32 s0, s76, 0x80000
	v_lshl_add_u64 v[184:185], s[76:77], 0, v[136:137]
	s_addc_u32 s1, s77, 0
	s_add_i32 s83, s84, s20
	global_load_lds_dwordx4 v[184:185], off
	v_lshl_add_u64 v[186:187], s[0:1], 0, v[132:133]
	s_mov_b32 m0, s83
	v_lshl_add_u64 v[224:225], s[78:79], 0, v[134:135]
	global_load_lds_dwordx4 v[186:187], off
	v_lshl_add_u64 v[186:187], s[0:1], 0, v[136:137]
	s_add_i32 m0, s83, 0x2000
	s_nop 0
	global_load_lds_dwordx4 v[186:187], off
	v_lshl_add_u64 v[186:187], s[78:79], 0, v[130:131]
	s_mov_b32 m0, s35
	s_nop 0
	global_load_lds_dwordx4 v[186:187], off
	s_mov_b32 m0, s37
	s_nop 0
	global_load_lds_dwordx4 v[224:225], off
	s_cmp_eq_u32 s27, 0
	s_cbranch_scc1 .Lw8_5
	s_waitcnt vmcnt(22)
	s_branch .Lwd_5

; #define PG8_STAGE(bufoff, gbase, voff) do { _Pragma("unroll") for (int _i = 0; _i < 2; ++_i) \
;         __builtin_amdgcn_global_load_lds((const unsigned*)((const char*)(gbase) + (voff)[_i]), (PG8_LAS unsigned*)(lds + (bufoff) + ldsw + _i * 8192), 16, 0, 0); } while (0)
; #define PG8_LDA(dst, b, h) do { _Pragma("unroll") for (int m = 0; m < 4; ++m) _Pragma("unroll") for (int k = 0; k < 2; ++k) dst[m][k] = *(const PG8_LAS bf16x8*)(lds + PG8_SA(b, h) + aoff + m * 2048 + k * 1024); } while (0)
; #define PG8_LDB(dst, b, h) do { _Pragma("unroll") for (int n = 0; n < 2; ++n) _Pragma("unroll") for (int k = 0; k < 2; ++k) dst[n][k] = *(const PG8_LAS bf16x8*)(lds + PG8_SB(b, h) + boff + n * 2048 + k * 1024); } while (0)
; #define PG8_WAIT_V(n) asm volatile("s_waitcnt vmcnt(" #n ")" ::: "memory")
; #define PG8_WAIT_L(n) asm volatile("s_waitcnt lgkmcnt(" #n ")" ::: "memory")
; #define PG8_BAR __builtin_amdgcn_s_barrier()
; #define PG8_SCHED __builtin_amdgcn_sched_barrier(0)
;     ...
;             PG8_WAIT_L(0); PG8_BAR; PG8_MMA(1, 0, At, B0); PG8_MMA(1, 1, At, B1); PG8_BAR; PG8_SCHED;
;             PG8_LDB(B0, 1, 0); PG8_LDB(B1, 1, 1); PG8_SCHED; PG8_LDA(At, 1, 0); PG8_STAGE(PG8_SA(0, 1), a2 + hstep, voffA);
;             PG8_WAIT_V(8); PG8_WAIT_L(0); PG8_BAR; PG8_MMA(0, 0, At, B0); PG8_MMA(0, 1, At, B1); PG8_BAR; PG8_SCHED;
.Lwd_5:
	s_waitcnt lgkmcnt(0)
	s_barrier
	s_setprio 1
	s_waitcnt lgkmcnt(0)
	v_mfma_f32_16x16x32_bf16 v[94:97], v[150:153], v[192:195], v[94:97]
	v_mfma_f32_16x16x32_bf16 v[78:81], v[158:161], v[192:195], v[78:81]
	v_mfma_f32_16x16x32_bf16 v[90:93], v[150:153], v[200:203], v[90:93]
	v_mfma_f32_16x16x32_bf16 v[74:77], v[158:161], v[200:203], v[74:77]
	v_mfma_f32_16x16x32_bf16 v[86:89], v[150:153], v[208:211], v[86:89]
	v_mfma_f32_16x16x32_bf16 v[62:65], v[158:161], v[208:211], v[62:65]
	v_mfma_f32_16x16x32_bf16 v[82:85], v[150:153], v[216:219], v[82:85]
	v_mfma_f32_16x16x32_bf16 v[54:57], v[158:161], v[216:219], v[54:57]
	v_mfma_f32_16x16x32_bf16 v[94:97], v[154:157], v[196:199], v[94:97]
	v_mfma_f32_16x16x32_bf16 v[78:81], v[162:165], v[196:199], v[78:81]
	v_mfma_f32_16x16x32_bf16 v[90:93], v[154:157], v[204:207], v[90:93]
	v_mfma_f32_16x16x32_bf16 v[74:77], v[162:165], v[204:207], v[74:77]
	v_mfma_f32_16x16x32_bf16 v[86:89], v[154:157], v[212:215], v[86:89]
	v_mfma_f32_16x16x32_bf16 v[62:65], v[162:165], v[212:215], v[62:65]
	v_mfma_f32_16x16x32_bf16 v[82:85], v[154:157], v[220:223], v[82:85]
	v_mfma_f32_16x16x32_bf16 v[54:57], v[162:165], v[220:223], v[54:57]
	s_setprio 0
	s_setprio 1
	v_mfma_f32_16x16x32_bf16 v[30:33], v[166:169], v[192:195], v[30:33]
	v_mfma_f32_16x16x32_bf16 v[14:17], v[176:179], v[192:195], v[14:17]
	v_mfma_f32_16x16x32_bf16 v[26:29], v[166:169], v[200:203], v[26:29]
	v_mfma_f32_16x16x32_bf16 v[10:13], v[176:179], v[200:203], v[10:13]
	v_mfma_f32_16x16x32_bf16 v[22:25], v[166:169], v[208:211], v[22:25]
	v_mfma_f32_16x16x32_bf16 v[6:9], v[176:179], v[208:211], v[6:9]
	v_mfma_f32_16x16x32_bf16 v[18:21], v[166:169], v[216:219], v[18:21]
	v_mfma_f32_16x16x32_bf16 v[2:5], v[176:179], v[216:219], v[2:5]
	v_mfma_f32_16x16x32_bf16 v[30:33], v[172:175], v[196:199], v[30:33]
	v_mfma_f32_16x16x32_bf16 v[14:17], v[188:191], v[196:199], v[14:17]
	v_mfma_f32_16x16x32_bf16 v[26:29], v[172:175], v[204:207], v[26:29]
	v_mfma_f32_16x16x32_bf16 v[10:13], v[188:191], v[204:207], v[10:13]
	v_mfma_f32_16x16x32_bf16 v[22:25], v[172:175], v[212:215], v[22:25]
	v_mfma_f32_16x16x32_bf16 v[6:9], v[188:191], v[212:215], v[6:9]
	v_mfma_f32_16x16x32_bf16 v[18:21], v[172:175], v[220:223], v[18:21]
	v_mfma_f32_16x16x32_bf16 v[2:5], v[188:191], v[220:223], v[2:5]
	s_setprio 0
	s_barrier
	s_add_i32 s83, 0, 0x18000
	v_add_u32_e32 v149, s83, v146
	s_add_i32 s84, 0, 0x1c000
	ds_read_b128 v[150:153], v149
	ds_read_b128 v[154:157], v149 offset:1024
	ds_read_b128 v[158:161], v149 offset:2048
	ds_read_b128 v[162:165], v149 offset:3072
	v_add_u32_e32 v149, s84, v146
	ds_read_b128 v[166:169], v149
	ds_read_b128 v[172:175], v149 offset:1024
	ds_read_b128 v[176:179], v149 offset:2048
	ds_read_b128 v[188:191], v149 offset:3072
	s_add_u32 s0, s78, 0x80000
	s_addc_u32 s1, s79, 0
	s_mov_b32 m0, s43
	v_lshl_add_u64 v[226:227], s[0:1], 0, v[130:131]
	ds_read_b128 v[192:195], v148 offset:32768
	ds_read_b128 v[196:199], v148 offset:33792
	ds_read_b128 v[200:203], v148 offset:34816
	ds_read_b128 v[204:207], v148 offset:35840
	ds_read_b128 v[208:211], v148 offset:36864
	ds_read_b128 v[212:215], v148 offset:37888
	ds_read_b128 v[216:219], v148 offset:38912
	ds_read_b128 v[220:223], v148 offset:39936
	global_load_lds_dwordx4 v[226:227], off
	v_lshl_add_u64 v[226:227], s[0:1], 0, v[134:135]
	s_mov_b32 m0, s44
	s_nop 0
	global_load_lds_dwordx4 v[226:227], off
	s_waitcnt vmcnt(8)
	s_waitcnt lgkmcnt(0)
	s_barrier
	s_setprio 1
	s_waitcnt lgkmcnt(0)
	v_mfma_f32_16x16x32_bf16 v[126:129], v[150:153], v[192:195], v[126:129]
	v_mfma_f32_16x16x32_bf16 v[110:113], v[158:161], v[192:195], v[110:113]
	v_mfma_f32_16x16x32_bf16 v[122:125], v[150:153], v[200:203], v[122:125]
	v_mfma_f32_16x16x32_bf16 v[106:109], v[158:161], v[200:203], v[106:109]
	v_mfma_f32_16x16x32_bf16 v[118:121], v[150:153], v[208:211], v[118:121]
	v_mfma_f32_16x16x32_bf16 v[102:105], v[158:161], v[208:211], v[102:105]
	v_mfma_f32_16x16x32_bf16 v[114:117], v[150:153], v[216:219], v[114:117]
	v_mfma_f32_16x16x32_bf16 v[98:101], v[158:161], v[216:219], v[98:101]
	v_mfma_f32_16x16x32_bf16 v[126:129], v[154:157], v[196:199], v[126:129]
	v_mfma_f32_16x16x32_bf16 v[110:113], v[162:165], v[196:199], v[110:113]
	v_mfma_f32_16x16x32_bf16 v[122:125], v[154:157], v[204:207], v[122:125]
	v_mfma_f32_16x16x32_bf16 v[106:109], v[162:165], v[204:207], v[106:109]
	v_mfma_f32_16x16x32_bf16 v[118:121], v[154:157], v[212:215], v[118:121]
	v_mfma_f32_16x16x32_bf16 v[102:105], v[162:165], v[212:215], v[102:105]
	v_mfma_f32_16x16x32_bf16 v[114:117], v[154:157], v[220:223], v[114:117]
	v_mfma_f32_16x16x32_bf16 v[98:101], v[162:165], v[220:223], v[98:101]
	s_setprio 0
	s_setprio 1
	v_mfma_f32_16x16x32_bf16 v[70:73], v[166:169], v[192:195], v[70:73]
	v_mfma_f32_16x16x32_bf16 v[50:53], v[176:179], v[192:195], v[50:53]
	v_mfma_f32_16x16x32_bf16 v[66:69], v[166:169], v[200:203], v[66:69]
	v_mfma_f32_16x16x32_bf16 v[42:45], v[176:179], v[200:203], v[42:45]
	v_mfma_f32_16x16x32_bf16 v[58:61], v[166:169], v[208:211], v[58:61]
	v_mfma_f32_16x16x32_bf16 v[38:41], v[176:179], v[208:211], v[38:41]
	v_mfma_f32_16x16x32_bf16 v[46:49], v[166:169], v[216:219], v[46:49]
	v_mfma_f32_16x16x32_bf16 v[34:37], v[176:179], v[216:219], v[34:37]
	v_mfma_f32_16x16x32_bf16 v[70:73], v[172:175], v[196:199], v[70:73]
	v_mfma_f32_16x16x32_bf16 v[50:53], v[188:191], v[196:199], v[50:53]
	v_mfma_f32_16x16x32_bf16 v[66:69], v[172:175], v[204:207], v[66:69]
	v_mfma_f32_16x16x32_bf16 v[42:45], v[188:191], v[204:207], v[42:45]
	v_mfma_f32_16x16x32_bf16 v[58:61], v[172:175], v[212:215], v[58:61]
	v_mfma_f32_16x16x32_bf16 v[38:41], v[188:191], v[212:215], v[38:41]
	v_mfma_f32_16x16x32_bf16 v[46:49], v[172:175], v[220:223], v[46:49]
	v_mfma_f32_16x16x32_bf16 v[34:37], v[188:191], v[220:223], v[34:37]
	s_setprio 0
	s_barrier
; #define PG8_STAGE(bufoff, gbase, voff) do { _Pragma("unroll") for (int _i = 0; _i < 2; ++_i) \
;         __builtin_amdgcn_global_load_lds((const unsigned*)((const char*)(gbase) + (voff)[_i]), (PG8_LAS unsigned*)(lds + (bufoff) + ldsw + _i * 8192), 16, 0, 0); } while (0)
; #define PG8_LDA(dst, b, h) do { _Pragma("unroll") for (int m = 0; m < 4; ++m) _Pragma("unroll") for (int k = 0; k < 2; ++k) dst[m][k] = *(const PG8_LAS bf16x8*)(lds + PG8_SA(b, h) + aoff + m * 2048 + k * 1024); } while (0)
; #define PG8_WAIT_V(n) asm volatile("s_waitcnt vmcnt(" #n ")" ::: "memory")
; #define PG8_WAIT_L(n) asm volatile("s_waitcnt lgkmcnt(" #n ")" ::: "memory")
;     ...
;         for (int t = 0; t < nt * KREP; t += 2) {
;             const bool last = (t == nt * KREP - 2);
;             const int t1w = KREP > 1 ? ((t + 1) & (nt - 1)) : t + 1, t2w = KREP > 1 ? ((t + 2) & (nt - 1)) : t + 2;
;             const char* a1 = cA + (size_t)t1w * kstep;
;             const char* a2 = last ? nA : cA + (size_t)t2w * kstep; const char* b2 = last ? nB : cB + (size_t)t2w * kstep;
;             const char* a3 = a2 + kstep; const char* b3 = b2 + kstep;
;             if (last && has_next) S.a_ready(nxt);
;             const int relax = __builtin_amdgcn_readfirstlane((MK_RELAXW && t == 0 && ui > 0) ? 1 : 0);
;             if constexpr (SP2) {
;             PG8_LDB(B0, 0, 0); PG8_LDB(B1, 0, 1); PG8_SCHED; PG8_LDA(At, 0, 0); PG8_STAGE(PG8_SA(1, 1), a1 + hstep, voffA);
;             PG8_WAIT_V_SEL(relax);
;             PG8_WAIT_L(0); PG8_BAR; PG8_MMA(0, 0, At, B0); PG8_MMA(0, 1, At, B1); PG8_BAR; PG8_SCHED;
;             PG8_LDA(At, 0, 1); PG8_STAGE(PG8_SB(0, 0), b2, voffB); PG8_STAGE(PG8_SB(0, 1), b2 + hstep, voffB); PG8_STAGE(PG8_SA(0, 0), a2, voffA);
;             PG8_WAIT_V_SEL(relax);
;             PG8_WAIT_L(0); PG8_BAR; PG8_MMA(1, 0, At, B0); PG8_MMA(1, 1, At, B1); PG8_BAR; PG8_SCHED;
;             PG8_LDB(B0, 1, 0); PG8_LDB(B1, 1, 1); PG8_SCHED; PG8_LDA(At, 1, 0); PG8_STAGE(PG8_SA(0, 1), a2 + hstep, voffA);
;             PG8_WAIT_V(8); PG8_WAIT_L(0); PG8_BAR; PG8_MMA(0, 0, At, B0); PG8_MMA(0, 1, At, B1); PG8_BAR; PG8_SCHED;
;             PG8_LDA(At, 1, 1); PG8_STAGE(PG8_SB(1, 0), b3, voffB); PG8_STAGE(PG8_SB(1, 1), b3 + hstep, voffB); PG8_STAGE(PG8_SA(1, 0), a3, voffA);
;             PG8_WAIT_V(8); PG8_WAIT_L(0); PG8_BAR; PG8_MMA(1, 0, At, B0); PG8_MMA(1, 1, At, B1); PG8_BAR; PG8_SCHED;
	s_add_i32 s0, s83, s20
	v_lshl_add_u64 v[180:181], v[180:181], 0, s[28:29]
	s_mov_b32 m0, s0
	ds_read_b128 v[192:195], v148 offset:49152
	ds_read_b128 v[196:199], v148 offset:50176
	ds_read_b128 v[200:203], v148 offset:51200
	ds_read_b128 v[204:207], v148 offset:52224
	ds_read_b128 v[208:211], v148 offset:53248
	ds_read_b128 v[212:215], v148 offset:54272
	ds_read_b128 v[216:219], v148 offset:55296
	ds_read_b128 v[220:223], v148 offset:56320
	global_load_lds_dwordx4 v[180:181], off
	s_add_i32 m0, s0, 0x2000
	s_add_u32 s0, s76, 0x80080
	v_lshl_add_u64 v[180:181], v[184:185], 0, s[28:29]
	s_addc_u32 s1, s77, 0
	s_add_i32 s76, s84, s20
	global_load_lds_dwordx4 v[180:181], off
	v_lshl_add_u64 v[180:181], s[0:1], 0, v[132:133]
	s_mov_b32 m0, s76
	s_nop 0
	global_load_lds_dwordx4 v[180:181], off
	v_lshl_add_u64 v[180:181], s[0:1], 0, v[136:137]
	s_add_i32 m0, s76, 0x2000
	s_nop 0
	global_load_lds_dwordx4 v[180:181], off
	v_lshl_add_u64 v[180:181], v[186:187], 0, s[28:29]
	s_mov_b32 m0, s48
	s_nop 0
	global_load_lds_dwordx4 v[180:181], off
	v_lshl_add_u64 v[180:181], v[224:225], 0, s[28:29]
	s_mov_b32 m0, s49
	s_nop 0
	global_load_lds_dwordx4 v[180:181], off
	s_waitcnt vmcnt(8)
	s_waitcnt lgkmcnt(0)
	s_barrier
	s_setprio 1
	s_waitcnt lgkmcnt(0)
	v_mfma_f32_16x16x32_bf16 v[94:97], v[150:153], v[192:195], v[94:97]
	v_mfma_f32_16x16x32_bf16 v[78:81], v[158:161], v[192:195], v[78:81]
	v_mfma_f32_16x16x32_bf16 v[90:93], v[150:153], v[200:203], v[90:93]
	v_mfma_f32_16x16x32_bf16 v[74:77], v[158:161], v[200:203], v[74:77]
	v_mfma_f32_16x16x32_bf16 v[86:89], v[150:153], v[208:211], v[86:89]
	v_mfma_f32_16x16x32_bf16 v[62:65], v[158:161], v[208:211], v[62:65]
	v_mfma_f32_16x16x32_bf16 v[82:85], v[150:153], v[216:219], v[82:85]
	v_mfma_f32_16x16x32_bf16 v[54:57], v[158:161], v[216:219], v[54:57]
	v_mfma_f32_16x16x32_bf16 v[94:97], v[154:157], v[196:199], v[94:97]
	v_mfma_f32_16x16x32_bf16 v[78:81], v[162:165], v[196:199], v[78:81]
	v_mfma_f32_16x16x32_bf16 v[90:93], v[154:157], v[204:207], v[90:93]
	v_mfma_f32_16x16x32_bf16 v[74:77], v[162:165], v[204:207], v[74:77]
	v_mfma_f32_16x16x32_bf16 v[86:89], v[154:157], v[212:215], v[86:89]
	v_mfma_f32_16x16x32_bf16 v[62:65], v[162:165], v[212:215], v[62:65]
	v_mfma_f32_16x16x32_bf16 v[82:85], v[154:157], v[220:223], v[82:85]
	v_mfma_f32_16x16x32_bf16 v[54:57], v[162:165], v[220:223], v[54:57]
	s_setprio 0
	s_setprio 1
	v_mfma_f32_16x16x32_bf16 v[30:33], v[166:169], v[192:195], v[30:33]
	v_mfma_f32_16x16x32_bf16 v[14:17], v[176:179], v[192:195], v[14:17]
	v_mfma_f32_16x16x32_bf16 v[26:29], v[166:169], v[200:203], v[26:29]
	v_mfma_f32_16x16x32_bf16 v[10:13], v[176:179], v[200:203], v[10:13]
	v_mfma_f32_16x16x32_bf16 v[22:25], v[166:169], v[208:211], v[22:25]
	v_mfma_f32_16x16x32_bf16 v[6:9], v[176:179], v[208:211], v[6:9]
	v_mfma_f32_16x16x32_bf16 v[18:21], v[166:169], v[216:219], v[18:21]
	v_mfma_f32_16x16x32_bf16 v[2:5], v[176:179], v[216:219], v[2:5]
	v_mfma_f32_16x16x32_bf16 v[30:33], v[172:175], v[196:199], v[30:33]
	v_mfma_f32_16x16x32_bf16 v[14:17], v[188:191], v[196:199], v[14:17]
	v_mfma_f32_16x16x32_bf16 v[26:29], v[172:175], v[204:207], v[26:29]
	v_mfma_f32_16x16x32_bf16 v[10:13], v[188:191], v[204:207], v[10:13]
	v_mfma_f32_16x16x32_bf16 v[22:25], v[172:175], v[212:215], v[22:25]
	v_mfma_f32_16x16x32_bf16 v[6:9], v[188:191], v[212:215], v[6:9]
	v_mfma_f32_16x16x32_bf16 v[18:21], v[172:175], v[220:223], v[18:21]
	v_mfma_f32_16x16x32_bf16 v[2:5], v[188:191], v[220:223], v[2:5]
	s_setprio 0
	s_barrier
	s_add_i32 s82, s82, 2
	s_add_u32 s74, s74, 0x100
	s_addc_u32 s75, s75, 0
	s_add_u32 s80, s80, 0x100
	s_addc_u32 s81, s81, 0
	s_cmp_gt_u32 s82, 29
	s_cbranch_scc0 .LBB0_596
	s_and_b64 vcc, exec, s[62:63]
	s_cbranch_vccz .LBB0_599
	s_barrier

; #define PG8_STAGE(bufoff, gbase, voff) do { _Pragma("unroll") for (int _i = 0; _i < 2; ++_i) \
;         __builtin_amdgcn_global_load_lds((const unsigned*)((const char*)(gbase) + (voff)[_i]), (PG8_LAS unsigned*)(lds + (bufoff) + ldsw + _i * 8192), 16, 0, 0); } while (0)
; #define PG8_LDA(dst, b, h) do { _Pragma("unroll") for (int m = 0; m < 4; ++m) _Pragma("unroll") for (int k = 0; k < 2; ++k) dst[m][k] = *(const PG8_LAS bf16x8*)(lds + PG8_SA(b, h) + aoff + m * 2048 + k * 1024); } while (0)
; #define PG8_LDB(dst, b, h) do { _Pragma("unroll") for (int n = 0; n < 2; ++n) _Pragma("unroll") for (int k = 0; k < 2; ++k) dst[n][k] = *(const PG8_LAS bf16x8*)(lds + PG8_SB(b, h) + boff + n * 2048 + k * 1024); } while (0)
; #define PG8_WAIT_L(n) asm volatile("s_waitcnt lgkmcnt(" #n ")" ::: "memory")
; #define PG8_WAIT_V_SEL(sel) asm volatile("s_cmp_eq_u32 %0, 0\n\ts_cbranch_scc1 .Lw8_%=\n\ts_waitcnt vmcnt(22)\n\ts_branch .Lwd_%=\n.Lw8_%=:\n\ts_waitcnt vmcnt(8)\n.Lwd_%=:" :: "s"(sel) : "memory", "scc")
; #define PG8_BAR __builtin_amdgcn_s_barrier()
; #define PG8_SCHED __builtin_amdgcn_sched_barrier(0)
;     ...
;             PG8_LDB(B0, 0, 0); PG8_LDB(B1, 0, 1); PG8_SCHED; PG8_LDA(At, 0, 0); PG8_STAGE(PG8_SA(1, 1), a1 + hstep, voffA);
;             PG8_WAIT_V_SEL(relax);
;             PG8_WAIT_L(0); PG8_BAR; PG8_MMA(0, 0, At, B0); PG8_MMA(0, 1, At, B1); PG8_BAR; PG8_SCHED;
;             PG8_LDA(At, 0, 1); PG8_STAGE(PG8_SB(0, 0), b2, voffB); PG8_STAGE(PG8_SB(0, 1), b2 + hstep, voffB); PG8_STAGE(PG8_SA(0, 0), a2, voffA);
;             PG8_WAIT_V_SEL(relax);
;             PG8_WAIT_L(0); PG8_BAR; PG8_MMA(1, 0, At, B0); PG8_MMA(1, 1, At, B1); PG8_BAR; PG8_SCHED;
.Lwd_6:
	s_waitcnt lgkmcnt(0)
	s_barrier
	s_setprio 1
	s_waitcnt lgkmcnt(0)
	v_mfma_f32_16x16x32_bf16 v[142:145], v[90:93], v[162:165], v[142:145]
	v_mfma_f32_16x16x32_bf16 v[138:141], v[98:101], v[162:165], v[138:141]
	v_mfma_f32_16x16x32_bf16 v[126:129], v[90:93], v[188:191], v[126:129]
	v_mfma_f32_16x16x32_bf16 v[122:125], v[98:101], v[188:191], v[122:125]
	v_mfma_f32_16x16x32_bf16 v[110:113], v[90:93], v[196:199], v[110:113]
	v_mfma_f32_16x16x32_bf16 v[106:109], v[98:101], v[196:199], v[106:109]
	v_mfma_f32_16x16x32_bf16 v[78:81], v[90:93], v[204:207], v[78:81]
	v_mfma_f32_16x16x32_bf16 v[74:77], v[98:101], v[204:207], v[74:77]
	v_mfma_f32_16x16x32_bf16 v[142:145], v[94:97], v[166:169], v[142:145]
	v_mfma_f32_16x16x32_bf16 v[138:141], v[102:105], v[166:169], v[138:141]
	v_mfma_f32_16x16x32_bf16 v[126:129], v[94:97], v[192:195], v[126:129]
	v_mfma_f32_16x16x32_bf16 v[122:125], v[102:105], v[192:195], v[122:125]
	v_mfma_f32_16x16x32_bf16 v[110:113], v[94:97], v[200:203], v[110:113]
	v_mfma_f32_16x16x32_bf16 v[106:109], v[102:105], v[200:203], v[106:109]
	v_mfma_f32_16x16x32_bf16 v[78:81], v[94:97], v[208:211], v[78:81]
	v_mfma_f32_16x16x32_bf16 v[74:77], v[102:105], v[208:211], v[74:77]
	s_setprio 0
	s_setprio 1
	v_mfma_f32_16x16x32_bf16 v[134:137], v[146:149], v[162:165], v[134:137]
	v_mfma_f32_16x16x32_bf16 v[130:133], v[154:157], v[162:165], v[130:133]
	v_mfma_f32_16x16x32_bf16 v[118:121], v[146:149], v[188:191], v[118:121]
	v_mfma_f32_16x16x32_bf16 v[114:117], v[154:157], v[188:191], v[114:117]
	v_mfma_f32_16x16x32_bf16 v[86:89], v[146:149], v[196:199], v[86:89]
	v_mfma_f32_16x16x32_bf16 v[82:85], v[154:157], v[196:199], v[82:85]
	v_mfma_f32_16x16x32_bf16 v[70:73], v[146:149], v[204:207], v[70:73]
	v_mfma_f32_16x16x32_bf16 v[66:69], v[154:157], v[204:207], v[66:69]
	v_mfma_f32_16x16x32_bf16 v[134:137], v[150:153], v[166:169], v[134:137]
	v_mfma_f32_16x16x32_bf16 v[130:133], v[158:161], v[166:169], v[130:133]
	v_mfma_f32_16x16x32_bf16 v[118:121], v[150:153], v[192:195], v[118:121]
	v_mfma_f32_16x16x32_bf16 v[114:117], v[158:161], v[192:195], v[114:117]
	v_mfma_f32_16x16x32_bf16 v[86:89], v[150:153], v[200:203], v[86:89]
	v_mfma_f32_16x16x32_bf16 v[82:85], v[158:161], v[200:203], v[82:85]
	v_mfma_f32_16x16x32_bf16 v[70:73], v[150:153], v[208:211], v[70:73]
	v_mfma_f32_16x16x32_bf16 v[66:69], v[158:161], v[208:211], v[66:69]
	s_setprio 0
	s_barrier
	s_add_i32 s0, s85, s33
	v_lshl_add_u64 v[184:185], s[80:81], 0, v[182:183]
	s_mov_b32 m0, s0
	ds_read_b128 v[162:165], v227 offset:16384
	ds_read_b128 v[166:169], v227 offset:17408
	ds_read_b128 v[188:191], v227 offset:18432
	ds_read_b128 v[192:195], v227 offset:19456
	ds_read_b128 v[196:199], v227 offset:20480
	ds_read_b128 v[200:203], v227 offset:21504
	ds_read_b128 v[204:207], v227 offset:22528
	ds_read_b128 v[208:211], v227 offset:23552
	global_load_lds_dwordx4 v[184:185], off
	s_add_i32 m0, s0, 0x2000
	s_add_u32 s0, s80, 0x80000
	v_lshl_add_u64 v[186:187], s[80:81], 0, v[176:177]
	s_addc_u32 s1, s81, 0
	s_add_i32 s85, s86, s33
	global_load_lds_dwordx4 v[186:187], off
	v_lshl_add_u64 v[212:213], s[0:1], 0, v[182:183]
	s_mov_b32 m0, s85
	v_lshl_add_u64 v[214:215], s[82:83], 0, v[174:175]
	global_load_lds_dwordx4 v[212:213], off
	v_lshl_add_u64 v[212:213], s[0:1], 0, v[176:177]
	s_add_i32 m0, s85, 0x2000
	s_nop 0
	global_load_lds_dwordx4 v[212:213], off
	v_lshl_add_u64 v[212:213], s[82:83], 0, v[172:173]
	s_mov_b32 m0, s45
	s_nop 0
	global_load_lds_dwordx4 v[212:213], off
	s_mov_b32 m0, s46
	s_nop 0
	global_load_lds_dwordx4 v[214:215], off
	s_cmp_eq_u32 s27, 0
	s_cbranch_scc1 .Lw8_7
	s_waitcnt vmcnt(22)
	s_branch .Lwd_7

; #define PG8_STAGE(bufoff, gbase, voff) do { _Pragma("unroll") for (int _i = 0; _i < 2; ++_i) \
;         __builtin_amdgcn_global_load_lds((const unsigned*)((const char*)(gbase) + (voff)[_i]), (PG8_LAS unsigned*)(lds + (bufoff) + ldsw + _i * 8192), 16, 0, 0); } while (0)
; #define PG8_LDA(dst, b, h) do { _Pragma("unroll") for (int m = 0; m < 4; ++m) _Pragma("unroll") for (int k = 0; k < 2; ++k) dst[m][k] = *(const PG8_LAS bf16x8*)(lds + PG8_SA(b, h) + aoff + m * 2048 + k * 1024); } while (0)
; #define PG8_LDB(dst, b, h) do { _Pragma("unroll") for (int n = 0; n < 2; ++n) _Pragma("unroll") for (int k = 0; k < 2; ++k) dst[n][k] = *(const PG8_LAS bf16x8*)(lds + PG8_SB(b, h) + boff + n * 2048 + k * 1024); } while (0)
; #define PG8_WAIT_V(n) asm volatile("s_waitcnt vmcnt(" #n ")" ::: "memory")
; #define PG8_WAIT_L(n) asm volatile("s_waitcnt lgkmcnt(" #n ")" ::: "memory")
; #define PG8_BAR __builtin_amdgcn_s_barrier()
; #define PG8_SCHED __builtin_amdgcn_sched_barrier(0)
;     ...
;             PG8_WAIT_L(0); PG8_BAR; PG8_MMA(1, 0, At, B0); PG8_MMA(1, 1, At, B1); PG8_BAR; PG8_SCHED;
;             PG8_LDB(B0, 1, 0); PG8_LDB(B1, 1, 1); PG8_SCHED; PG8_LDA(At, 1, 0); PG8_STAGE(PG8_SA(0, 1), a2 + hstep, voffA);
;             PG8_WAIT_V(8); PG8_WAIT_L(0); PG8_BAR; PG8_MMA(0, 0, At, B0); PG8_MMA(0, 1, At, B1); PG8_BAR; PG8_SCHED;
;             PG8_LDA(At, 1, 1); PG8_STAGE(PG8_SB(1, 0), b3, voffB); PG8_STAGE(PG8_SB(1, 1), b3 + hstep, voffB); PG8_STAGE(PG8_SA(1, 0), a3, voffA);
;             PG8_WAIT_V(8); PG8_WAIT_L(0); PG8_BAR; PG8_MMA(1, 0, At, B0); PG8_MMA(1, 1, At, B1); PG8_BAR; PG8_SCHED;
.Lwd_7:
	s_waitcnt lgkmcnt(0)
	s_barrier
	s_setprio 1
	s_waitcnt lgkmcnt(0)
	v_mfma_f32_16x16x32_bf16 v[62:65], v[90:93], v[162:165], v[62:65]
	v_mfma_f32_16x16x32_bf16 v[58:61], v[98:101], v[162:165], v[58:61]
	v_mfma_f32_16x16x32_bf16 v[46:49], v[90:93], v[188:191], v[46:49]
	v_mfma_f32_16x16x32_bf16 v[42:45], v[98:101], v[188:191], v[42:45]
	v_mfma_f32_16x16x32_bf16 v[30:33], v[90:93], v[196:199], v[30:33]
	v_mfma_f32_16x16x32_bf16 v[26:29], v[98:101], v[196:199], v[26:29]
	v_mfma_f32_16x16x32_bf16 v[14:17], v[90:93], v[204:207], v[14:17]
	v_mfma_f32_16x16x32_bf16 v[10:13], v[98:101], v[204:207], v[10:13]
	v_mfma_f32_16x16x32_bf16 v[62:65], v[94:97], v[166:169], v[62:65]
	v_mfma_f32_16x16x32_bf16 v[58:61], v[102:105], v[166:169], v[58:61]
	v_mfma_f32_16x16x32_bf16 v[46:49], v[94:97], v[192:195], v[46:49]
	v_mfma_f32_16x16x32_bf16 v[42:45], v[102:105], v[192:195], v[42:45]
	v_mfma_f32_16x16x32_bf16 v[30:33], v[94:97], v[200:203], v[30:33]
	v_mfma_f32_16x16x32_bf16 v[26:29], v[102:105], v[200:203], v[26:29]
	v_mfma_f32_16x16x32_bf16 v[14:17], v[94:97], v[208:211], v[14:17]
	v_mfma_f32_16x16x32_bf16 v[10:13], v[102:105], v[208:211], v[10:13]
	s_setprio 0
	s_setprio 1
	v_mfma_f32_16x16x32_bf16 v[54:57], v[146:149], v[162:165], v[54:57]
	v_mfma_f32_16x16x32_bf16 v[50:53], v[154:157], v[162:165], v[50:53]
	v_mfma_f32_16x16x32_bf16 v[38:41], v[146:149], v[188:191], v[38:41]
	v_mfma_f32_16x16x32_bf16 v[34:37], v[154:157], v[188:191], v[34:37]
	v_mfma_f32_16x16x32_bf16 v[22:25], v[146:149], v[196:199], v[22:25]
	v_mfma_f32_16x16x32_bf16 v[18:21], v[154:157], v[196:199], v[18:21]
	v_mfma_f32_16x16x32_bf16 v[6:9], v[146:149], v[204:207], v[6:9]
	v_mfma_f32_16x16x32_bf16 v[2:5], v[154:157], v[204:207], v[2:5]
	v_mfma_f32_16x16x32_bf16 v[54:57], v[150:153], v[166:169], v[54:57]
	v_mfma_f32_16x16x32_bf16 v[50:53], v[158:161], v[166:169], v[50:53]
	v_mfma_f32_16x16x32_bf16 v[38:41], v[150:153], v[192:195], v[38:41]
	v_mfma_f32_16x16x32_bf16 v[34:37], v[158:161], v[192:195], v[34:37]
	v_mfma_f32_16x16x32_bf16 v[22:25], v[150:153], v[200:203], v[22:25]
	v_mfma_f32_16x16x32_bf16 v[18:21], v[158:161], v[200:203], v[18:21]
	v_mfma_f32_16x16x32_bf16 v[6:9], v[150:153], v[208:211], v[6:9]
	v_mfma_f32_16x16x32_bf16 v[2:5], v[158:161], v[208:211], v[2:5]
	s_setprio 0
	s_barrier
	s_add_i32 s85, 0, 0x18000
	s_add_i32 s86, 0, 0x1c000
	v_add_u32_e32 v102, s85, v224
	v_add_u32_e32 v158, s86, v224
	ds_read_b128 v[90:93], v102
	ds_read_b128 v[94:97], v102 offset:1024
	ds_read_b128 v[98:101], v102 offset:2048
	ds_read_b128 v[102:105], v102 offset:3072
	ds_read_b128 v[146:149], v158
	ds_read_b128 v[150:153], v158 offset:1024
	ds_read_b128 v[154:157], v158 offset:2048
	ds_read_b128 v[158:161], v158 offset:3072
	s_add_u32 s0, s82, 0x80000
	s_addc_u32 s1, s83, 0
	s_mov_b32 m0, s47
	v_lshl_add_u64 v[216:217], s[0:1], 0, v[172:173]
	ds_read_b128 v[162:165], v227 offset:32768
	ds_read_b128 v[166:169], v227 offset:33792
	ds_read_b128 v[188:191], v227 offset:34816
	ds_read_b128 v[192:195], v227 offset:35840
	ds_read_b128 v[196:199], v227 offset:36864
	ds_read_b128 v[200:203], v227 offset:37888
	ds_read_b128 v[204:207], v227 offset:38912
	ds_read_b128 v[208:211], v227 offset:39936
	global_load_lds_dwordx4 v[216:217], off
	v_lshl_add_u64 v[216:217], s[0:1], 0, v[174:175]
	s_mov_b32 m0, s48
	s_nop 0
	global_load_lds_dwordx4 v[216:217], off
	s_waitcnt vmcnt(8)
	s_waitcnt lgkmcnt(0)
	s_barrier
	s_setprio 1
	s_waitcnt lgkmcnt(0)
	v_mfma_f32_16x16x32_bf16 v[142:145], v[90:93], v[162:165], v[142:145]
	v_mfma_f32_16x16x32_bf16 v[138:141], v[98:101], v[162:165], v[138:141]
	v_mfma_f32_16x16x32_bf16 v[126:129], v[90:93], v[188:191], v[126:129]
	v_mfma_f32_16x16x32_bf16 v[122:125], v[98:101], v[188:191], v[122:125]
	v_mfma_f32_16x16x32_bf16 v[110:113], v[90:93], v[196:199], v[110:113]
	v_mfma_f32_16x16x32_bf16 v[106:109], v[98:101], v[196:199], v[106:109]
	v_mfma_f32_16x16x32_bf16 v[78:81], v[90:93], v[204:207], v[78:81]
	v_mfma_f32_16x16x32_bf16 v[74:77], v[98:101], v[204:207], v[74:77]
	v_mfma_f32_16x16x32_bf16 v[142:145], v[94:97], v[166:169], v[142:145]
	v_mfma_f32_16x16x32_bf16 v[138:141], v[102:105], v[166:169], v[138:141]
	v_mfma_f32_16x16x32_bf16 v[126:129], v[94:97], v[192:195], v[126:129]
	v_mfma_f32_16x16x32_bf16 v[122:125], v[102:105], v[192:195], v[122:125]
	v_mfma_f32_16x16x32_bf16 v[110:113], v[94:97], v[200:203], v[110:113]
	v_mfma_f32_16x16x32_bf16 v[106:109], v[102:105], v[200:203], v[106:109]
	v_mfma_f32_16x16x32_bf16 v[78:81], v[94:97], v[208:211], v[78:81]
	v_mfma_f32_16x16x32_bf16 v[74:77], v[102:105], v[208:211], v[74:77]
	s_setprio 0
	s_setprio 1
	v_mfma_f32_16x16x32_bf16 v[134:137], v[146:149], v[162:165], v[134:137]
	v_mfma_f32_16x16x32_bf16 v[130:133], v[154:157], v[162:165], v[130:133]
	v_mfma_f32_16x16x32_bf16 v[118:121], v[146:149], v[188:191], v[118:121]
	v_mfma_f32_16x16x32_bf16 v[114:117], v[154:157], v[188:191], v[114:117]
	v_mfma_f32_16x16x32_bf16 v[86:89], v[146:149], v[196:199], v[86:89]
	v_mfma_f32_16x16x32_bf16 v[82:85], v[154:157], v[196:199], v[82:85]
	v_mfma_f32_16x16x32_bf16 v[70:73], v[146:149], v[204:207], v[70:73]
	v_mfma_f32_16x16x32_bf16 v[66:69], v[154:157], v[204:207], v[66:69]
	v_mfma_f32_16x16x32_bf16 v[134:137], v[150:153], v[166:169], v[134:137]
	v_mfma_f32_16x16x32_bf16 v[130:133], v[158:161], v[166:169], v[130:133]
	v_mfma_f32_16x16x32_bf16 v[118:121], v[150:153], v[192:195], v[118:121]
	v_mfma_f32_16x16x32_bf16 v[114:117], v[158:161], v[192:195], v[114:117]
	v_mfma_f32_16x16x32_bf16 v[86:89], v[150:153], v[200:203], v[86:89]
	v_mfma_f32_16x16x32_bf16 v[82:85], v[158:161], v[200:203], v[82:85]
	v_mfma_f32_16x16x32_bf16 v[70:73], v[150:153], v[208:211], v[70:73]
	v_mfma_f32_16x16x32_bf16 v[66:69], v[158:161], v[208:211], v[66:69]
	s_setprio 0
	s_barrier
; #define PG8_STAGE(bufoff, gbase, voff) do { _Pragma("unroll") for (int _i = 0; _i < 2; ++_i) \
;         __builtin_amdgcn_global_load_lds((const unsigned*)((const char*)(gbase) + (voff)[_i]), (PG8_LAS unsigned*)(lds + (bufoff) + ldsw + _i * 8192), 16, 0, 0); } while (0)
; #define PG8_LDA(dst, b, h) do { _Pragma("unroll") for (int m = 0; m < 4; ++m) _Pragma("unroll") for (int k = 0; k < 2; ++k) dst[m][k] = *(const PG8_LAS bf16x8*)(lds + PG8_SA(b, h) + aoff + m * 2048 + k * 1024); } while (0)
; #define PG8_WAIT_V(n) asm volatile("s_waitcnt vmcnt(" #n ")" ::: "memory")
; #define PG8_WAIT_L(n) asm volatile("s_waitcnt lgkmcnt(" #n ")" ::: "memory")
; #define PG8_BAR __builtin_amdgcn_s_barrier()
; #define PG8_SCHED __builtin_amdgcn_sched_barrier(0)
;     ...
;         for (int t = 0; t < nt * KREP; t += 2) {
;             const bool last = (t == nt * KREP - 2);
;             const int t1w = KREP > 1 ? ((t + 1) & (nt - 1)) : t + 1, t2w = KREP > 1 ? ((t + 2) & (nt - 1)) : t + 2;
;             const char* a1 = cA + (size_t)t1w * kstep;
;             const char* a2 = last ? nA : cA + (size_t)t2w * kstep; const char* b2 = last ? nB : cB + (size_t)t2w * kstep;
;     ...
;             PG8_LDA(At, 1, 1); PG8_STAGE(PG8_SB(1, 0), b3, voffB); PG8_STAGE(PG8_SB(1, 1), b3 + hstep, voffB); PG8_STAGE(PG8_SA(1, 0), a3, voffA);
;             PG8_WAIT_V(8); PG8_WAIT_L(0); PG8_BAR; PG8_MMA(1, 0, At, B0); PG8_MMA(1, 1, At, B1); PG8_BAR; PG8_SCHED;
	s_add_i32 s0, s85, s33
	v_lshl_add_u64 v[184:185], v[184:185], 0, s[28:29]
	s_mov_b32 m0, s0
	ds_read_b128 v[162:165], v227 offset:49152
	ds_read_b128 v[166:169], v227 offset:50176
	ds_read_b128 v[188:191], v227 offset:51200
	ds_read_b128 v[192:195], v227 offset:52224
	ds_read_b128 v[196:199], v227 offset:53248
	ds_read_b128 v[200:203], v227 offset:54272
	ds_read_b128 v[204:207], v227 offset:55296
	ds_read_b128 v[208:211], v227 offset:56320
	global_load_lds_dwordx4 v[184:185], off
	s_add_i32 m0, s0, 0x2000
	s_add_u32 s0, s80, 0x80080
	v_lshl_add_u64 v[184:185], v[186:187], 0, s[28:29]
	s_addc_u32 s1, s81, 0
	s_add_i32 s80, s86, s33
	global_load_lds_dwordx4 v[184:185], off
	v_lshl_add_u64 v[184:185], s[0:1], 0, v[182:183]
	s_mov_b32 m0, s80
	s_nop 0
	global_load_lds_dwordx4 v[184:185], off
	v_lshl_add_u64 v[184:185], s[0:1], 0, v[176:177]
	s_add_i32 m0, s80, 0x2000
	s_nop 0
	global_load_lds_dwordx4 v[184:185], off
	v_lshl_add_u64 v[184:185], v[212:213], 0, s[28:29]
	s_mov_b32 m0, s50
	s_nop 0
	global_load_lds_dwordx4 v[184:185], off
	v_lshl_add_u64 v[184:185], v[214:215], 0, s[28:29]
	s_mov_b32 m0, s51
	s_nop 0
	global_load_lds_dwordx4 v[184:185], off
	s_waitcnt vmcnt(8)
	s_waitcnt lgkmcnt(0)
	s_barrier
	s_setprio 1
	s_waitcnt lgkmcnt(0)
	v_mfma_f32_16x16x32_bf16 v[62:65], v[90:93], v[162:165], v[62:65]
	v_mfma_f32_16x16x32_bf16 v[58:61], v[98:101], v[162:165], v[58:61]
	v_mfma_f32_16x16x32_bf16 v[46:49], v[90:93], v[188:191], v[46:49]
	v_mfma_f32_16x16x32_bf16 v[42:45], v[98:101], v[188:191], v[42:45]
	v_mfma_f32_16x16x32_bf16 v[30:33], v[90:93], v[196:199], v[30:33]
	v_mfma_f32_16x16x32_bf16 v[26:29], v[98:101], v[196:199], v[26:29]
	v_mfma_f32_16x16x32_bf16 v[14:17], v[90:93], v[204:207], v[14:17]
	v_mfma_f32_16x16x32_bf16 v[10:13], v[98:101], v[204:207], v[10:13]
	v_mfma_f32_16x16x32_bf16 v[62:65], v[94:97], v[166:169], v[62:65]
	v_mfma_f32_16x16x32_bf16 v[58:61], v[102:105], v[166:169], v[58:61]
	v_mfma_f32_16x16x32_bf16 v[46:49], v[94:97], v[192:195], v[46:49]
	v_mfma_f32_16x16x32_bf16 v[42:45], v[102:105], v[192:195], v[42:45]
	v_mfma_f32_16x16x32_bf16 v[30:33], v[94:97], v[200:203], v[30:33]
	v_mfma_f32_16x16x32_bf16 v[26:29], v[102:105], v[200:203], v[26:29]
	v_mfma_f32_16x16x32_bf16 v[14:17], v[94:97], v[208:211], v[14:17]
	v_mfma_f32_16x16x32_bf16 v[10:13], v[102:105], v[208:211], v[10:13]
	s_setprio 0
	s_setprio 1
	v_mfma_f32_16x16x32_bf16 v[54:57], v[146:149], v[162:165], v[54:57]
	v_mfma_f32_16x16x32_bf16 v[50:53], v[154:157], v[162:165], v[50:53]
	v_mfma_f32_16x16x32_bf16 v[38:41], v[146:149], v[188:191], v[38:41]
	v_mfma_f32_16x16x32_bf16 v[34:37], v[154:157], v[188:191], v[34:37]
	v_mfma_f32_16x16x32_bf16 v[22:25], v[146:149], v[196:199], v[22:25]
	v_mfma_f32_16x16x32_bf16 v[18:21], v[154:157], v[196:199], v[18:21]
	v_mfma_f32_16x16x32_bf16 v[6:9], v[146:149], v[204:207], v[6:9]
	v_mfma_f32_16x16x32_bf16 v[2:5], v[154:157], v[204:207], v[2:5]
	v_mfma_f32_16x16x32_bf16 v[54:57], v[150:153], v[166:169], v[54:57]
	v_mfma_f32_16x16x32_bf16 v[50:53], v[158:161], v[166:169], v[50:53]
	v_mfma_f32_16x16x32_bf16 v[38:41], v[150:153], v[192:195], v[38:41]
	v_mfma_f32_16x16x32_bf16 v[34:37], v[158:161], v[192:195], v[34:37]
	v_mfma_f32_16x16x32_bf16 v[22:25], v[150:153], v[200:203], v[22:25]
	v_mfma_f32_16x16x32_bf16 v[18:21], v[158:161], v[200:203], v[18:21]
	v_mfma_f32_16x16x32_bf16 v[6:9], v[150:153], v[208:211], v[6:9]
	v_mfma_f32_16x16x32_bf16 v[2:5], v[158:161], v[208:211], v[2:5]
	s_setprio 0
	s_barrier
	s_add_i32 s84, s84, 2
	s_add_u32 s78, s78, 0x100
	s_addc_u32 s79, s79, 0
	s_add_u32 s75, s75, 0x100
	s_addc_u32 s77, s77, 0
	s_cmp_gt_u32 s84, 29
	s_cbranch_scc0 .LBB0_1170
	s_and_b64 vcc, exec, s[64:65]
	s_cbranch_vccz .LBB0_1173
	s_barrier

; #define PG8_STAGE(bufoff, gbase, voff) do { _Pragma("unroll") for (int _i = 0; _i < 2; ++_i) \
;         __builtin_amdgcn_global_load_lds((const unsigned*)((const char*)(gbase) + (voff)[_i]), (PG8_LAS unsigned*)(lds + (bufoff) + ldsw + _i * 8192), 16, 0, 0); } while (0)
; #define PG8_LDA(dst, b, h) do { _Pragma("unroll") for (int m = 0; m < 4; ++m) _Pragma("unroll") for (int k = 0; k < 2; ++k) dst[m][k] = *(const PG8_LAS bf16x8*)(lds + PG8_SA(b, h) + aoff + m * 2048 + k * 1024); } while (0)
; #define PG8_LDB(dst, b, h) do { _Pragma("unroll") for (int n = 0; n < 2; ++n) _Pragma("unroll") for (int k = 0; k < 2; ++k) dst[n][k] = *(const PG8_LAS bf16x8*)(lds + PG8_SB(b, h) + boff + n * 2048 + k * 1024); } while (0)
; #define PG8_WAIT_L(n) asm volatile("s_waitcnt lgkmcnt(" #n ")" ::: "memory")
; #define PG8_WAIT_V_SEL(sel) asm volatile("s_cmp_eq_u32 %0, 0\n\ts_cbranch_scc1 .Lw8_%=\n\ts_waitcnt vmcnt(22)\n\ts_branch .Lwd_%=\n.Lw8_%=:\n\ts_waitcnt vmcnt(8)\n.Lwd_%=:" :: "s"(sel) : "memory", "scc")
; #define PG8_BAR __builtin_amdgcn_s_barrier()
; #define PG8_SCHED __builtin_amdgcn_sched_barrier(0)
;     ...
;             PG8_LDB(B0, 0, 0); PG8_LDB(B1, 0, 1); PG8_SCHED; PG8_LDA(At, 0, 0); PG8_STAGE(PG8_SA(1, 1), a1 + hstep, voffA);
;             PG8_WAIT_V_SEL(relax);
;             PG8_WAIT_L(0); PG8_BAR; PG8_MMA(0, 0, At, B0); PG8_MMA(0, 1, At, B1); PG8_BAR; PG8_SCHED;
;             PG8_LDA(At, 0, 1); PG8_STAGE(PG8_SB(0, 0), b2, voffB); PG8_STAGE(PG8_SB(0, 1), b2 + hstep, voffB); PG8_STAGE(PG8_SA(0, 0), a2, voffA);
;             PG8_WAIT_V_SEL(relax);
;             PG8_WAIT_L(0); PG8_BAR; PG8_MMA(1, 0, At, B0); PG8_MMA(1, 1, At, B1); PG8_BAR; PG8_SCHED;
.Lwd_8:
	s_waitcnt lgkmcnt(0)
	s_barrier
	s_setprio 1
	s_waitcnt lgkmcnt(0)
	v_mfma_f32_16x16x32_bf16 v[114:117], v[66:69], v[162:165], v[114:117]
	v_mfma_f32_16x16x32_bf16 v[106:109], v[82:85], v[162:165], v[106:109]
	v_mfma_f32_16x16x32_bf16 v[110:113], v[66:69], v[170:173], v[110:113]
	v_mfma_f32_16x16x32_bf16 v[102:105], v[82:85], v[170:173], v[102:105]
	v_mfma_f32_16x16x32_bf16 v[78:81], v[66:69], v[178:181], v[78:81]
	v_mfma_f32_16x16x32_bf16 v[138:141], v[82:85], v[178:181], v[138:141]
	v_mfma_f32_16x16x32_bf16 v[74:77], v[66:69], v[220:223], v[74:77]
	v_mfma_f32_16x16x32_bf16 v[134:137], v[82:85], v[220:223], v[134:137]
	v_mfma_f32_16x16x32_bf16 v[114:117], v[70:73], v[166:169], v[114:117]
	v_mfma_f32_16x16x32_bf16 v[106:109], v[142:145], v[166:169], v[106:109]
	v_mfma_f32_16x16x32_bf16 v[110:113], v[70:73], v[174:177], v[110:113]
	v_mfma_f32_16x16x32_bf16 v[102:105], v[142:145], v[174:177], v[102:105]
	v_mfma_f32_16x16x32_bf16 v[78:81], v[70:73], v[184:187], v[78:81]
	v_mfma_f32_16x16x32_bf16 v[138:141], v[142:145], v[184:187], v[138:141]
	v_mfma_f32_16x16x32_bf16 v[74:77], v[70:73], v[224:227], v[74:77]
	v_mfma_f32_16x16x32_bf16 v[134:137], v[142:145], v[224:227], v[134:137]
	s_setprio 0
	s_setprio 1
	v_mfma_f32_16x16x32_bf16 v[98:101], v[146:149], v[162:165], v[98:101]
	v_mfma_f32_16x16x32_bf16 v[90:93], v[154:157], v[162:165], v[90:93]
	v_mfma_f32_16x16x32_bf16 v[94:97], v[146:149], v[170:173], v[94:97]
	v_mfma_f32_16x16x32_bf16 v[86:89], v[154:157], v[170:173], v[86:89]
	v_mfma_f32_16x16x32_bf16 v[130:133], v[146:149], v[178:181], v[130:133]
	v_mfma_f32_16x16x32_bf16 v[122:125], v[154:157], v[178:181], v[122:125]
	v_mfma_f32_16x16x32_bf16 v[126:129], v[146:149], v[220:223], v[126:129]
	v_mfma_f32_16x16x32_bf16 v[118:121], v[154:157], v[220:223], v[118:121]
	v_mfma_f32_16x16x32_bf16 v[98:101], v[150:153], v[166:169], v[98:101]
	v_mfma_f32_16x16x32_bf16 v[90:93], v[158:161], v[166:169], v[90:93]
	v_mfma_f32_16x16x32_bf16 v[94:97], v[150:153], v[174:177], v[94:97]
	v_mfma_f32_16x16x32_bf16 v[86:89], v[158:161], v[174:177], v[86:89]
	v_mfma_f32_16x16x32_bf16 v[130:133], v[150:153], v[184:187], v[130:133]
	v_mfma_f32_16x16x32_bf16 v[122:125], v[158:161], v[184:187], v[122:125]
	v_mfma_f32_16x16x32_bf16 v[126:129], v[150:153], v[224:227], v[126:129]
	v_mfma_f32_16x16x32_bf16 v[118:121], v[158:161], v[224:227], v[118:121]
	s_setprio 0
	v_mfma_f32_16x16x32_bf16 v[242:245], v[66:69], v[162:165], v[242:245]
	v_mfma_f32_16x16x32_bf16 v[246:249], v[82:85], v[170:173], v[246:249]
	v_mfma_f32_16x16x32_bf16 v[242:245], v[70:73], v[178:181], v[242:245]
	v_mfma_f32_16x16x32_bf16 v[246:249], v[142:145], v[220:223], v[246:249]
	v_mfma_f32_16x16x32_bf16 v[242:245], v[146:149], v[166:169], v[242:245]
	v_mfma_f32_16x16x32_bf16 v[246:249], v[154:157], v[174:177], v[246:249]
	v_mfma_f32_16x16x32_bf16 v[242:245], v[150:153], v[184:187], v[242:245]
	v_mfma_f32_16x16x32_bf16 v[246:249], v[158:161], v[224:227], v[246:249]
	s_barrier
	s_add_i32 s12, s51, s37
	v_lshl_add_u64 v[200:201], vcc, 0, v[182:183]
	s_mov_b32 m0, s12
	ds_read_b128 v[162:165], v219 offset:16384
	ds_read_b128 v[166:169], v219 offset:17408
	ds_read_b128 v[170:173], v219 offset:18432
	ds_read_b128 v[174:177], v219 offset:19456
	ds_read_b128 v[178:181], v219 offset:20480
	ds_read_b128 v[184:187], v219 offset:21504
	ds_read_b128 v[220:223], v219 offset:22528
	ds_read_b128 v[224:227], v219 offset:23552
	global_load_lds_dwordx4 v[200:201], off
	s_add_i32 m0, s12, 0x2000
	s_add_u32 s12, vcc_lo, 0x80000
	v_lshl_add_u64 v[228:229], vcc, 0, v[192:193]
	s_addc_u32 s13, vcc_hi, 0
	s_add_i32 s19, s19, s37
	global_load_lds_dwordx4 v[228:229], off
	v_lshl_add_u64 v[230:231], s[12:13], 0, v[182:183]
	s_mov_b32 m0, s19
	v_lshl_add_u64 v[236:237], s[40:41], 0, v[190:191]
	global_load_lds_dwordx4 v[230:231], off
	v_lshl_add_u64 v[230:231], s[12:13], 0, v[192:193]
	s_add_i32 m0, s19, 0x2000
	s_nop 0
	global_load_lds_dwordx4 v[230:231], off
	v_lshl_add_u64 v[230:231], s[40:41], 0, v[188:189]
	s_mov_b32 m0, s95
	s_nop 0
	global_load_lds_dwordx4 v[230:231], off
	s_mov_b32 m0, s20
	s_nop 0
	global_load_lds_dwordx4 v[236:237], off
	s_cmp_eq_u32 s27, 0
	s_cbranch_scc1 .Lw8_9
	s_waitcnt vmcnt(22)
	s_branch .Lwd_9

; #define PG8_STAGE(bufoff, gbase, voff) do { _Pragma("unroll") for (int _i = 0; _i < 2; ++_i) \
;         __builtin_amdgcn_global_load_lds((const unsigned*)((const char*)(gbase) + (voff)[_i]), (PG8_LAS unsigned*)(lds + (bufoff) + ldsw + _i * 8192), 16, 0, 0); } while (0)
; #define PG8_LDA(dst, b, h) do { _Pragma("unroll") for (int m = 0; m < 4; ++m) _Pragma("unroll") for (int k = 0; k < 2; ++k) dst[m][k] = *(const PG8_LAS bf16x8*)(lds + PG8_SA(b, h) + aoff + m * 2048 + k * 1024); } while (0)
; #define PG8_LDB(dst, b, h) do { _Pragma("unroll") for (int n = 0; n < 2; ++n) _Pragma("unroll") for (int k = 0; k < 2; ++k) dst[n][k] = *(const PG8_LAS bf16x8*)(lds + PG8_SB(b, h) + boff + n * 2048 + k * 1024); } while (0)
; #define PG8_WAIT_V(n) asm volatile("s_waitcnt vmcnt(" #n ")" ::: "memory")
; #define PG8_WAIT_L(n) asm volatile("s_waitcnt lgkmcnt(" #n ")" ::: "memory")
; #define PG8_BAR __builtin_amdgcn_s_barrier()
; #define PG8_SCHED __builtin_amdgcn_sched_barrier(0)
;     ...
;             PG8_WAIT_L(0); PG8_BAR; PG8_MMA(1, 0, At, B0); PG8_MMA(1, 1, At, B1); PG8_BAR; PG8_SCHED;
;             PG8_LDB(B0, 1, 0); PG8_LDB(B1, 1, 1); PG8_SCHED; PG8_LDA(At, 1, 0); PG8_STAGE(PG8_SA(0, 1), a2 + hstep, voffA);
;             PG8_WAIT_V(8); PG8_WAIT_L(0); PG8_BAR; PG8_MMA(0, 0, At, B0); PG8_MMA(0, 1, At, B1); PG8_BAR; PG8_SCHED;
;             PG8_LDA(At, 1, 1); PG8_STAGE(PG8_SB(1, 0), b3, voffB); PG8_STAGE(PG8_SB(1, 1), b3 + hstep, voffB); PG8_STAGE(PG8_SA(1, 0), a3, voffA);
;             PG8_WAIT_V(8); PG8_WAIT_L(0); PG8_BAR; PG8_MMA(1, 0, At, B0); PG8_MMA(1, 1, At, B1); PG8_BAR; PG8_SCHED;
.Lwd_9:
	s_waitcnt lgkmcnt(0)
	s_barrier
	s_setprio 1
	s_waitcnt lgkmcnt(0)
	v_mfma_f32_16x16x32_bf16 v[30:33], v[66:69], v[162:165], v[30:33]
	v_mfma_f32_16x16x32_bf16 v[22:25], v[82:85], v[162:165], v[22:25]
	v_mfma_f32_16x16x32_bf16 v[26:29], v[66:69], v[170:173], v[26:29]
	v_mfma_f32_16x16x32_bf16 v[18:21], v[82:85], v[170:173], v[18:21]
	v_mfma_f32_16x16x32_bf16 v[62:65], v[66:69], v[178:181], v[62:65]
	v_mfma_f32_16x16x32_bf16 v[54:57], v[82:85], v[178:181], v[54:57]
	v_mfma_f32_16x16x32_bf16 v[58:61], v[66:69], v[220:223], v[58:61]
	v_mfma_f32_16x16x32_bf16 v[50:53], v[82:85], v[220:223], v[50:53]
	v_mfma_f32_16x16x32_bf16 v[30:33], v[70:73], v[166:169], v[30:33]
	v_mfma_f32_16x16x32_bf16 v[22:25], v[142:145], v[166:169], v[22:25]
	v_mfma_f32_16x16x32_bf16 v[26:29], v[70:73], v[174:177], v[26:29]
	v_mfma_f32_16x16x32_bf16 v[18:21], v[142:145], v[174:177], v[18:21]
	v_mfma_f32_16x16x32_bf16 v[62:65], v[70:73], v[184:187], v[62:65]
	v_mfma_f32_16x16x32_bf16 v[54:57], v[142:145], v[184:187], v[54:57]
	v_mfma_f32_16x16x32_bf16 v[58:61], v[70:73], v[224:227], v[58:61]
	v_mfma_f32_16x16x32_bf16 v[50:53], v[142:145], v[224:227], v[50:53]
	s_setprio 0
	s_setprio 1
	v_mfma_f32_16x16x32_bf16 v[14:17], v[146:149], v[162:165], v[14:17]
	v_mfma_f32_16x16x32_bf16 v[6:9], v[154:157], v[162:165], v[6:9]
	v_mfma_f32_16x16x32_bf16 v[10:13], v[146:149], v[170:173], v[10:13]
	v_mfma_f32_16x16x32_bf16 v[2:5], v[154:157], v[170:173], v[2:5]
	v_mfma_f32_16x16x32_bf16 v[46:49], v[146:149], v[178:181], v[46:49]
	v_mfma_f32_16x16x32_bf16 v[34:37], v[154:157], v[178:181], v[34:37]
	v_mfma_f32_16x16x32_bf16 v[38:41], v[146:149], v[220:223], v[38:41]
	v_mfma_f32_16x16x32_bf16 v[42:45], v[154:157], v[220:223], v[42:45]
	v_mfma_f32_16x16x32_bf16 v[14:17], v[150:153], v[166:169], v[14:17]
	v_mfma_f32_16x16x32_bf16 v[6:9], v[158:161], v[166:169], v[6:9]
	v_mfma_f32_16x16x32_bf16 v[10:13], v[150:153], v[174:177], v[10:13]
	v_mfma_f32_16x16x32_bf16 v[2:5], v[158:161], v[174:177], v[2:5]
	v_mfma_f32_16x16x32_bf16 v[46:49], v[150:153], v[184:187], v[46:49]
	v_mfma_f32_16x16x32_bf16 v[34:37], v[158:161], v[184:187], v[34:37]
	v_mfma_f32_16x16x32_bf16 v[38:41], v[150:153], v[224:227], v[38:41]
	v_mfma_f32_16x16x32_bf16 v[42:45], v[158:161], v[224:227], v[42:45]
	s_setprio 0
	v_mfma_f32_16x16x32_bf16 v[242:245], v[66:69], v[162:165], v[242:245]
	v_mfma_f32_16x16x32_bf16 v[246:249], v[82:85], v[170:173], v[246:249]
	v_mfma_f32_16x16x32_bf16 v[242:245], v[70:73], v[178:181], v[242:245]
	v_mfma_f32_16x16x32_bf16 v[246:249], v[142:145], v[220:223], v[246:249]
	v_mfma_f32_16x16x32_bf16 v[242:245], v[146:149], v[166:169], v[242:245]
	v_mfma_f32_16x16x32_bf16 v[246:249], v[154:157], v[174:177], v[246:249]
	v_mfma_f32_16x16x32_bf16 v[242:245], v[150:153], v[184:187], v[242:245]
	v_mfma_f32_16x16x32_bf16 v[246:249], v[158:161], v[224:227], v[246:249]
	s_barrier
	s_add_i32 s19, 0, 0x18000
	s_add_i32 s51, 0, 0x1c000
	v_add_u32_e32 v142, s19, v203
	v_add_u32_e32 v158, s51, v203
	ds_read_b128 v[66:69], v142
	ds_read_b128 v[70:73], v142 offset:1024
	ds_read_b128 v[82:85], v142 offset:2048
	ds_read_b128 v[142:145], v142 offset:3072
	ds_read_b128 v[146:149], v158
	ds_read_b128 v[150:153], v158 offset:1024
	ds_read_b128 v[154:157], v158 offset:2048
	ds_read_b128 v[158:161], v158 offset:3072
	s_add_u32 s12, s40, 0x80000
	s_addc_u32 s13, s41, 0
	s_mov_b32 m0, s44
	v_lshl_add_u64 v[238:239], s[12:13], 0, v[188:189]
	ds_read_b128 v[162:165], v219 offset:32768
	ds_read_b128 v[166:169], v219 offset:33792
	ds_read_b128 v[170:173], v219 offset:34816
	ds_read_b128 v[174:177], v219 offset:35840
	ds_read_b128 v[178:181], v219 offset:36864
	ds_read_b128 v[184:187], v219 offset:37888
	ds_read_b128 v[220:223], v219 offset:38912
	ds_read_b128 v[224:227], v219 offset:39936
	global_load_lds_dwordx4 v[238:239], off
	v_lshl_add_u64 v[238:239], s[12:13], 0, v[190:191]
	s_mov_b32 m0, s46
	s_nop 0
	global_load_lds_dwordx4 v[238:239], off
	s_waitcnt vmcnt(8)
	s_waitcnt lgkmcnt(0)
	s_barrier
	s_setprio 1
	s_waitcnt lgkmcnt(0)
	v_mfma_f32_16x16x32_bf16 v[114:117], v[66:69], v[162:165], v[114:117]
	v_mfma_f32_16x16x32_bf16 v[106:109], v[82:85], v[162:165], v[106:109]
	v_mfma_f32_16x16x32_bf16 v[110:113], v[66:69], v[170:173], v[110:113]
	v_mfma_f32_16x16x32_bf16 v[102:105], v[82:85], v[170:173], v[102:105]
	v_mfma_f32_16x16x32_bf16 v[78:81], v[66:69], v[178:181], v[78:81]
	v_mfma_f32_16x16x32_bf16 v[138:141], v[82:85], v[178:181], v[138:141]
	v_mfma_f32_16x16x32_bf16 v[74:77], v[66:69], v[220:223], v[74:77]
	v_mfma_f32_16x16x32_bf16 v[134:137], v[82:85], v[220:223], v[134:137]
	v_mfma_f32_16x16x32_bf16 v[114:117], v[70:73], v[166:169], v[114:117]
	v_mfma_f32_16x16x32_bf16 v[106:109], v[142:145], v[166:169], v[106:109]
	v_mfma_f32_16x16x32_bf16 v[110:113], v[70:73], v[174:177], v[110:113]
	v_mfma_f32_16x16x32_bf16 v[102:105], v[142:145], v[174:177], v[102:105]
	v_mfma_f32_16x16x32_bf16 v[78:81], v[70:73], v[184:187], v[78:81]
	v_mfma_f32_16x16x32_bf16 v[138:141], v[142:145], v[184:187], v[138:141]
	v_mfma_f32_16x16x32_bf16 v[74:77], v[70:73], v[224:227], v[74:77]
	v_mfma_f32_16x16x32_bf16 v[134:137], v[142:145], v[224:227], v[134:137]
	s_setprio 0
	s_setprio 1
	v_mfma_f32_16x16x32_bf16 v[98:101], v[146:149], v[162:165], v[98:101]
	v_mfma_f32_16x16x32_bf16 v[90:93], v[154:157], v[162:165], v[90:93]
	v_mfma_f32_16x16x32_bf16 v[94:97], v[146:149], v[170:173], v[94:97]
	v_mfma_f32_16x16x32_bf16 v[86:89], v[154:157], v[170:173], v[86:89]
	v_mfma_f32_16x16x32_bf16 v[130:133], v[146:149], v[178:181], v[130:133]
	v_mfma_f32_16x16x32_bf16 v[122:125], v[154:157], v[178:181], v[122:125]
	v_mfma_f32_16x16x32_bf16 v[126:129], v[146:149], v[220:223], v[126:129]
	v_mfma_f32_16x16x32_bf16 v[118:121], v[154:157], v[220:223], v[118:121]
	v_mfma_f32_16x16x32_bf16 v[98:101], v[150:153], v[166:169], v[98:101]
	v_mfma_f32_16x16x32_bf16 v[90:93], v[158:161], v[166:169], v[90:93]
	v_mfma_f32_16x16x32_bf16 v[94:97], v[150:153], v[174:177], v[94:97]
	v_mfma_f32_16x16x32_bf16 v[86:89], v[158:161], v[174:177], v[86:89]
	v_mfma_f32_16x16x32_bf16 v[130:133], v[150:153], v[184:187], v[130:133]
	v_mfma_f32_16x16x32_bf16 v[122:125], v[158:161], v[184:187], v[122:125]
	v_mfma_f32_16x16x32_bf16 v[126:129], v[150:153], v[224:227], v[126:129]
	v_mfma_f32_16x16x32_bf16 v[118:121], v[158:161], v[224:227], v[118:121]
	s_setprio 0
	v_mfma_f32_16x16x32_bf16 v[242:245], v[66:69], v[162:165], v[242:245]
	v_mfma_f32_16x16x32_bf16 v[246:249], v[82:85], v[170:173], v[246:249]
	v_mfma_f32_16x16x32_bf16 v[242:245], v[70:73], v[178:181], v[242:245]
	v_mfma_f32_16x16x32_bf16 v[246:249], v[142:145], v[220:223], v[246:249]
	v_mfma_f32_16x16x32_bf16 v[242:245], v[146:149], v[166:169], v[242:245]
	v_mfma_f32_16x16x32_bf16 v[246:249], v[154:157], v[174:177], v[246:249]
	v_mfma_f32_16x16x32_bf16 v[242:245], v[150:153], v[184:187], v[242:245]
	v_mfma_f32_16x16x32_bf16 v[246:249], v[158:161], v[224:227], v[246:249]
	s_barrier
; #define PG8_STAGE(bufoff, gbase, voff) do { _Pragma("unroll") for (int _i = 0; _i < 2; ++_i) \
;         __builtin_amdgcn_global_load_lds((const unsigned*)((const char*)(gbase) + (voff)[_i]), (PG8_LAS unsigned*)(lds + (bufoff) + ldsw + _i * 8192), 16, 0, 0); } while (0)
; #define PG8_LDA(dst, b, h) do { _Pragma("unroll") for (int m = 0; m < 4; ++m) _Pragma("unroll") for (int k = 0; k < 2; ++k) dst[m][k] = *(const PG8_LAS bf16x8*)(lds + PG8_SA(b, h) + aoff + m * 2048 + k * 1024); } while (0)
; #define PG8_WAIT_V(n) asm volatile("s_waitcnt vmcnt(" #n ")" ::: "memory")
; #define PG8_WAIT_L(n) asm volatile("s_waitcnt lgkmcnt(" #n ")" ::: "memory")
; #define PG8_BAR __builtin_amdgcn_s_barrier()
; #define PG8_SCHED __builtin_amdgcn_sched_barrier(0)
;     ...
;         for (int t = 0; t < nt * KREP; t += 2) {
;             const bool last = (t == nt * KREP - 2);
;             const int t1w = KREP > 1 ? ((t + 1) & (nt - 1)) : t + 1, t2w = KREP > 1 ? ((t + 2) & (nt - 1)) : t + 2;
;             const char* a1 = cA + (size_t)t1w * kstep;
;             const char* a2 = last ? nA : cA + (size_t)t2w * kstep; const char* b2 = last ? nB : cB + (size_t)t2w * kstep;
;     ...
;             PG8_LDA(At, 1, 1); PG8_STAGE(PG8_SB(1, 0), b3, voffB); PG8_STAGE(PG8_SB(1, 1), b3 + hstep, voffB); PG8_STAGE(PG8_SA(1, 0), a3, voffA);
;             PG8_WAIT_V(8); PG8_WAIT_L(0); PG8_BAR; PG8_MMA(1, 0, At, B0); PG8_MMA(1, 1, At, B1); PG8_BAR; PG8_SCHED;
	s_add_i32 s12, s19, s37
	v_lshl_add_u64 v[200:201], v[200:201], 0, s[28:29]
	s_mov_b32 m0, s12
	ds_read_b128 v[162:165], v219 offset:49152
	ds_read_b128 v[166:169], v219 offset:50176
	ds_read_b128 v[170:173], v219 offset:51200
	ds_read_b128 v[174:177], v219 offset:52224
	ds_read_b128 v[178:181], v219 offset:53248
	ds_read_b128 v[184:187], v219 offset:54272
	ds_read_b128 v[220:223], v219 offset:55296
	ds_read_b128 v[224:227], v219 offset:56320
	global_load_lds_dwordx4 v[200:201], off
	s_add_i32 m0, s12, 0x2000
	s_add_u32 s12, vcc_lo, 0x80080
	v_lshl_add_u64 v[200:201], v[228:229], 0, s[28:29]
	s_addc_u32 s13, vcc_hi, 0
	s_add_i32 s19, s51, s37
	global_load_lds_dwordx4 v[200:201], off
	v_lshl_add_u64 v[200:201], s[12:13], 0, v[182:183]
	s_mov_b32 m0, s19
	s_nop 0
	global_load_lds_dwordx4 v[200:201], off
	v_lshl_add_u64 v[200:201], s[12:13], 0, v[192:193]
	s_add_i32 m0, s19, 0x2000
	s_nop 0
	global_load_lds_dwordx4 v[200:201], off
	v_lshl_add_u64 v[200:201], v[230:231], 0, s[28:29]
	s_mov_b32 m0, s45
	s_nop 0
	global_load_lds_dwordx4 v[200:201], off
	v_lshl_add_u64 v[200:201], v[236:237], 0, s[28:29]
	s_mov_b32 m0, s24
	s_nop 0
	global_load_lds_dwordx4 v[200:201], off
	s_waitcnt vmcnt(8)
	s_waitcnt lgkmcnt(0)
	s_barrier
	s_setprio 1
	s_waitcnt lgkmcnt(0)
	v_mfma_f32_16x16x32_bf16 v[30:33], v[66:69], v[162:165], v[30:33]
	v_mfma_f32_16x16x32_bf16 v[22:25], v[82:85], v[162:165], v[22:25]
	v_mfma_f32_16x16x32_bf16 v[26:29], v[66:69], v[170:173], v[26:29]
	v_mfma_f32_16x16x32_bf16 v[18:21], v[82:85], v[170:173], v[18:21]
	v_mfma_f32_16x16x32_bf16 v[62:65], v[66:69], v[178:181], v[62:65]
	v_mfma_f32_16x16x32_bf16 v[54:57], v[82:85], v[178:181], v[54:57]
	v_mfma_f32_16x16x32_bf16 v[58:61], v[66:69], v[220:223], v[58:61]
	v_mfma_f32_16x16x32_bf16 v[50:53], v[82:85], v[220:223], v[50:53]
	v_mfma_f32_16x16x32_bf16 v[30:33], v[70:73], v[166:169], v[30:33]
	v_mfma_f32_16x16x32_bf16 v[22:25], v[142:145], v[166:169], v[22:25]
	v_mfma_f32_16x16x32_bf16 v[26:29], v[70:73], v[174:177], v[26:29]
	v_mfma_f32_16x16x32_bf16 v[18:21], v[142:145], v[174:177], v[18:21]
	v_mfma_f32_16x16x32_bf16 v[62:65], v[70:73], v[184:187], v[62:65]
	v_mfma_f32_16x16x32_bf16 v[54:57], v[142:145], v[184:187], v[54:57]
	v_mfma_f32_16x16x32_bf16 v[58:61], v[70:73], v[224:227], v[58:61]
	v_mfma_f32_16x16x32_bf16 v[50:53], v[142:145], v[224:227], v[50:53]
	s_setprio 0
	s_setprio 1
	v_mfma_f32_16x16x32_bf16 v[14:17], v[146:149], v[162:165], v[14:17]
	v_mfma_f32_16x16x32_bf16 v[6:9], v[154:157], v[162:165], v[6:9]
	v_mfma_f32_16x16x32_bf16 v[10:13], v[146:149], v[170:173], v[10:13]
	v_mfma_f32_16x16x32_bf16 v[2:5], v[154:157], v[170:173], v[2:5]
	v_mfma_f32_16x16x32_bf16 v[46:49], v[146:149], v[178:181], v[46:49]
	v_mfma_f32_16x16x32_bf16 v[34:37], v[154:157], v[178:181], v[34:37]
	v_mfma_f32_16x16x32_bf16 v[38:41], v[146:149], v[220:223], v[38:41]
	v_mfma_f32_16x16x32_bf16 v[42:45], v[154:157], v[220:223], v[42:45]
	v_mfma_f32_16x16x32_bf16 v[14:17], v[150:153], v[166:169], v[14:17]
	v_mfma_f32_16x16x32_bf16 v[6:9], v[158:161], v[166:169], v[6:9]
	v_mfma_f32_16x16x32_bf16 v[10:13], v[150:153], v[174:177], v[10:13]
	v_mfma_f32_16x16x32_bf16 v[2:5], v[158:161], v[174:177], v[2:5]
	v_mfma_f32_16x16x32_bf16 v[46:49], v[150:153], v[184:187], v[46:49]
	v_mfma_f32_16x16x32_bf16 v[34:37], v[158:161], v[184:187], v[34:37]
	v_mfma_f32_16x16x32_bf16 v[38:41], v[150:153], v[224:227], v[38:41]
	v_mfma_f32_16x16x32_bf16 v[42:45], v[158:161], v[224:227], v[42:45]
	s_setprio 0
	v_mfma_f32_16x16x32_bf16 v[242:245], v[66:69], v[162:165], v[242:245]
	v_mfma_f32_16x16x32_bf16 v[246:249], v[82:85], v[170:173], v[246:249]
	v_mfma_f32_16x16x32_bf16 v[242:245], v[70:73], v[178:181], v[242:245]
	v_mfma_f32_16x16x32_bf16 v[246:249], v[142:145], v[220:223], v[246:249]
	v_mfma_f32_16x16x32_bf16 v[242:245], v[146:149], v[166:169], v[242:245]
	v_mfma_f32_16x16x32_bf16 v[246:249], v[154:157], v[174:177], v[246:249]
	v_mfma_f32_16x16x32_bf16 v[242:245], v[150:153], v[184:187], v[242:245]
	v_mfma_f32_16x16x32_bf16 v[246:249], v[158:161], v[224:227], v[246:249]
	s_barrier
	s_add_i32 s0, s0, 2
	s_add_u32 s66, s66, 0x100
	s_addc_u32 s67, s67, 0
	s_cmp_gt_u32 s0, 29
	s_mov_b64 s[12:13], s[96:97]
	s_cbranch_scc0 .LBB0_1327
	s_and_b64 vcc, exec, s[78:79]
	s_cbranch_vccz .LBB0_1330
	s_barrier

; #define PG8_STAGE(bufoff, gbase, voff) do { _Pragma("unroll") for (int _i = 0; _i < 2; ++_i) \
;         __builtin_amdgcn_global_load_lds((const unsigned*)((const char*)(gbase) + (voff)[_i]), (PG8_LAS unsigned*)(lds + (bufoff) + ldsw + _i * 8192), 16, 0, 0); } while (0)
; #define PG8_LDA(dst, b, h) do { _Pragma("unroll") for (int m = 0; m < 4; ++m) _Pragma("unroll") for (int k = 0; k < 2; ++k) dst[m][k] = *(const PG8_LAS bf16x8*)(lds + PG8_SA(b, h) + aoff + m * 2048 + k * 1024); } while (0)
; #define PG8_LDB(dst, b, h) do { _Pragma("unroll") for (int n = 0; n < 2; ++n) _Pragma("unroll") for (int k = 0; k < 2; ++k) dst[n][k] = *(const PG8_LAS bf16x8*)(lds + PG8_SB(b, h) + boff + n * 2048 + k * 1024); } while (0)
; #define PG8_WAIT_L(n) asm volatile("s_waitcnt lgkmcnt(" #n ")" ::: "memory")
; #define PG8_WAIT_V_SEL(sel) asm volatile("s_cmp_eq_u32 %0, 0\n\ts_cbranch_scc1 .Lw8_%=\n\ts_waitcnt vmcnt(22)\n\ts_branch .Lwd_%=\n.Lw8_%=:\n\ts_waitcnt vmcnt(8)\n.Lwd_%=:" :: "s"(sel) : "memory", "scc")
; #define PG8_BAR __builtin_amdgcn_s_barrier()
; #define PG8_SCHED __builtin_amdgcn_sched_barrier(0)
;     ...
;             PG8_LDB(B0, 0, 0); PG8_LDB(B1, 0, 1); PG8_SCHED; PG8_LDA(At, 0, 0); PG8_STAGE(PG8_SA(1, 1), a1 + hstep, voffA);
;             PG8_WAIT_V_SEL(relax);
;             PG8_WAIT_L(0); PG8_BAR; PG8_MMA(0, 0, At, B0); PG8_MMA(0, 1, At, B1); PG8_BAR; PG8_SCHED;
;             PG8_LDA(At, 0, 1); PG8_STAGE(PG8_SB(0, 0), b2, voffB); PG8_STAGE(PG8_SB(0, 1), b2 + hstep, voffB); PG8_STAGE(PG8_SA(0, 0), a2, voffA);
;             PG8_WAIT_V_SEL(relax);
;             PG8_WAIT_L(0); PG8_BAR; PG8_MMA(1, 0, At, B0); PG8_MMA(1, 1, At, B1); PG8_BAR; PG8_SCHED;
.Lwd_10:
	s_waitcnt lgkmcnt(0)
	s_barrier
	s_setprio 1
	s_waitcnt lgkmcnt(0)
	v_mfma_f32_16x16x32_bf16 v[150:153], v[58:61], v[162:165], v[150:153]
	v_mfma_f32_16x16x32_bf16 v[146:149], v[74:77], v[162:165], v[146:149]
	v_mfma_f32_16x16x32_bf16 v[126:129], v[58:61], v[170:173], v[126:129]
	v_mfma_f32_16x16x32_bf16 v[122:125], v[74:77], v[170:173], v[122:125]
	v_mfma_f32_16x16x32_bf16 v[110:113], v[58:61], v[184:187], v[110:113]
	v_mfma_f32_16x16x32_bf16 v[106:109], v[74:77], v[184:187], v[106:109]
	v_mfma_f32_16x16x32_bf16 v[94:97], v[58:61], v[198:201], v[94:97]
	v_mfma_f32_16x16x32_bf16 v[90:93], v[74:77], v[198:201], v[90:93]
	v_mfma_f32_16x16x32_bf16 v[150:153], v[62:65], v[166:169], v[150:153]
	v_mfma_f32_16x16x32_bf16 v[146:149], v[78:81], v[166:169], v[146:149]
	v_mfma_f32_16x16x32_bf16 v[126:129], v[62:65], v[174:177], v[126:129]
	v_mfma_f32_16x16x32_bf16 v[122:125], v[78:81], v[174:177], v[122:125]
	v_mfma_f32_16x16x32_bf16 v[110:113], v[62:65], v[194:197], v[110:113]
	v_mfma_f32_16x16x32_bf16 v[106:109], v[78:81], v[194:197], v[106:109]
	v_mfma_f32_16x16x32_bf16 v[94:97], v[62:65], v[202:205], v[94:97]
	v_mfma_f32_16x16x32_bf16 v[90:93], v[78:81], v[202:205], v[90:93]
	s_setprio 0
	s_setprio 1
	v_mfma_f32_16x16x32_bf16 v[138:141], v[130:133], v[162:165], v[138:141]
	v_mfma_f32_16x16x32_bf16 v[134:137], v[154:157], v[162:165], v[134:137]
	v_mfma_f32_16x16x32_bf16 v[118:121], v[130:133], v[170:173], v[118:121]
	v_mfma_f32_16x16x32_bf16 v[114:117], v[154:157], v[170:173], v[114:117]
	v_mfma_f32_16x16x32_bf16 v[102:105], v[130:133], v[184:187], v[102:105]
	v_mfma_f32_16x16x32_bf16 v[98:101], v[154:157], v[184:187], v[98:101]
	v_mfma_f32_16x16x32_bf16 v[86:89], v[130:133], v[198:201], v[86:89]
	v_mfma_f32_16x16x32_bf16 v[82:85], v[154:157], v[198:201], v[82:85]
	v_mfma_f32_16x16x32_bf16 v[138:141], v[142:145], v[166:169], v[138:141]
	v_mfma_f32_16x16x32_bf16 v[134:137], v[158:161], v[166:169], v[134:137]
	v_mfma_f32_16x16x32_bf16 v[118:121], v[142:145], v[174:177], v[118:121]
	v_mfma_f32_16x16x32_bf16 v[114:117], v[158:161], v[174:177], v[114:117]
	v_mfma_f32_16x16x32_bf16 v[102:105], v[142:145], v[194:197], v[102:105]
	v_mfma_f32_16x16x32_bf16 v[98:101], v[158:161], v[194:197], v[98:101]
	v_mfma_f32_16x16x32_bf16 v[86:89], v[142:145], v[202:205], v[86:89]
	v_mfma_f32_16x16x32_bf16 v[82:85], v[158:161], v[202:205], v[82:85]
	s_setprio 0
	s_barrier
	s_add_i32 s8, s46, s90
	v_lshl_add_u64 v[206:207], s[80:81], 0, v[182:183]
	s_mov_b32 m0, s8
	ds_read_b128 v[162:165], v246 offset:16384
	ds_read_b128 v[166:169], v246 offset:17408
	ds_read_b128 v[170:173], v246 offset:18432
	ds_read_b128 v[174:177], v246 offset:19456
	ds_read_b128 v[184:187], v246 offset:20480
	ds_read_b128 v[194:197], v246 offset:21504
	ds_read_b128 v[198:201], v246 offset:22528
	ds_read_b128 v[202:205], v246 offset:23552
	global_load_lds_dwordx4 v[206:207], off
	s_add_i32 m0, s8, 0x2000
	s_add_u32 s8, s80, 0x158000
	v_lshl_add_u64 v[208:209], s[80:81], 0, v[188:189]
	s_addc_u32 s9, s81, 0
	s_add_i32 s46, s47, s90
	global_load_lds_dwordx4 v[208:209], off
	v_lshl_add_u64 v[210:211], s[8:9], 0, v[182:183]
	s_mov_b32 m0, s46
	v_lshl_add_u64 v[212:213], s[40:41], 0, v[180:181]
	global_load_lds_dwordx4 v[210:211], off
	v_lshl_add_u64 v[210:211], s[8:9], 0, v[188:189]
	s_add_i32 m0, s46, 0x2000
	s_nop 0
	global_load_lds_dwordx4 v[210:211], off
	v_lshl_add_u64 v[210:211], s[40:41], 0, v[178:179]
	s_mov_b32 m0, s91
	s_nop 0
	global_load_lds_dwordx4 v[210:211], off
	s_mov_b32 m0, s92
	s_nop 0
	global_load_lds_dwordx4 v[212:213], off
	s_cmp_eq_u32 s27, 0
	s_cbranch_scc1 .Lw8_11
	s_waitcnt vmcnt(22)
	s_branch .Lwd_11

; #define PG8_STAGE(bufoff, gbase, voff) do { _Pragma("unroll") for (int _i = 0; _i < 2; ++_i) \
;         __builtin_amdgcn_global_load_lds((const unsigned*)((const char*)(gbase) + (voff)[_i]), (PG8_LAS unsigned*)(lds + (bufoff) + ldsw + _i * 8192), 16, 0, 0); } while (0)
; #define PG8_LDA(dst, b, h) do { _Pragma("unroll") for (int m = 0; m < 4; ++m) _Pragma("unroll") for (int k = 0; k < 2; ++k) dst[m][k] = *(const PG8_LAS bf16x8*)(lds + PG8_SA(b, h) + aoff + m * 2048 + k * 1024); } while (0)
; #define PG8_LDB(dst, b, h) do { _Pragma("unroll") for (int n = 0; n < 2; ++n) _Pragma("unroll") for (int k = 0; k < 2; ++k) dst[n][k] = *(const PG8_LAS bf16x8*)(lds + PG8_SB(b, h) + boff + n * 2048 + k * 1024); } while (0)
; #define PG8_WAIT_V(n) asm volatile("s_waitcnt vmcnt(" #n ")" ::: "memory")
; #define PG8_WAIT_L(n) asm volatile("s_waitcnt lgkmcnt(" #n ")" ::: "memory")
; #define PG8_BAR __builtin_amdgcn_s_barrier()
; #define PG8_SCHED __builtin_amdgcn_sched_barrier(0)
;     ...
;             PG8_WAIT_L(0); PG8_BAR; PG8_MMA(1, 0, At, B0); PG8_MMA(1, 1, At, B1); PG8_BAR; PG8_SCHED;
;             PG8_LDB(B0, 1, 0); PG8_LDB(B1, 1, 1); PG8_SCHED; PG8_LDA(At, 1, 0); PG8_STAGE(PG8_SA(0, 1), a2 + hstep, voffA);
;             PG8_WAIT_V(8); PG8_WAIT_L(0); PG8_BAR; PG8_MMA(0, 0, At, B0); PG8_MMA(0, 1, At, B1); PG8_BAR; PG8_SCHED;
;             PG8_LDA(At, 1, 1); PG8_STAGE(PG8_SB(1, 0), b3, voffB); PG8_STAGE(PG8_SB(1, 1), b3 + hstep, voffB); PG8_STAGE(PG8_SA(1, 0), a3, voffA);
;             PG8_WAIT_V(8); PG8_WAIT_L(0); PG8_BAR; PG8_MMA(1, 0, At, B0); PG8_MMA(1, 1, At, B1); PG8_BAR; PG8_SCHED;
.Lwd_11:
	s_waitcnt lgkmcnt(0)
	s_barrier
	s_setprio 1
	s_waitcnt lgkmcnt(0)
	v_mfma_f32_16x16x32_bf16 v[70:73], v[58:61], v[162:165], v[70:73]
	v_mfma_f32_16x16x32_bf16 v[66:69], v[74:77], v[162:165], v[66:69]
	v_mfma_f32_16x16x32_bf16 v[46:49], v[58:61], v[170:173], v[46:49]
	v_mfma_f32_16x16x32_bf16 v[42:45], v[74:77], v[170:173], v[42:45]
	v_mfma_f32_16x16x32_bf16 v[30:33], v[58:61], v[184:187], v[30:33]
	v_mfma_f32_16x16x32_bf16 v[26:29], v[74:77], v[184:187], v[26:29]
	v_mfma_f32_16x16x32_bf16 v[14:17], v[58:61], v[198:201], v[14:17]
	v_mfma_f32_16x16x32_bf16 v[10:13], v[74:77], v[198:201], v[10:13]
	v_mfma_f32_16x16x32_bf16 v[70:73], v[62:65], v[166:169], v[70:73]
	v_mfma_f32_16x16x32_bf16 v[66:69], v[78:81], v[166:169], v[66:69]
	v_mfma_f32_16x16x32_bf16 v[46:49], v[62:65], v[174:177], v[46:49]
	v_mfma_f32_16x16x32_bf16 v[42:45], v[78:81], v[174:177], v[42:45]
	v_mfma_f32_16x16x32_bf16 v[30:33], v[62:65], v[194:197], v[30:33]
	v_mfma_f32_16x16x32_bf16 v[26:29], v[78:81], v[194:197], v[26:29]
	v_mfma_f32_16x16x32_bf16 v[14:17], v[62:65], v[202:205], v[14:17]
	v_mfma_f32_16x16x32_bf16 v[10:13], v[78:81], v[202:205], v[10:13]
	s_setprio 0
	s_setprio 1
	v_mfma_f32_16x16x32_bf16 v[54:57], v[130:133], v[162:165], v[54:57]
	v_mfma_f32_16x16x32_bf16 v[50:53], v[154:157], v[162:165], v[50:53]
	v_mfma_f32_16x16x32_bf16 v[38:41], v[130:133], v[170:173], v[38:41]
	v_mfma_f32_16x16x32_bf16 v[34:37], v[154:157], v[170:173], v[34:37]
	v_mfma_f32_16x16x32_bf16 v[22:25], v[130:133], v[184:187], v[22:25]
	v_mfma_f32_16x16x32_bf16 v[18:21], v[154:157], v[184:187], v[18:21]
	v_mfma_f32_16x16x32_bf16 v[6:9], v[130:133], v[198:201], v[6:9]
	v_mfma_f32_16x16x32_bf16 v[2:5], v[154:157], v[198:201], v[2:5]
	v_mfma_f32_16x16x32_bf16 v[54:57], v[142:145], v[166:169], v[54:57]
	v_mfma_f32_16x16x32_bf16 v[50:53], v[158:161], v[166:169], v[50:53]
	v_mfma_f32_16x16x32_bf16 v[38:41], v[142:145], v[174:177], v[38:41]
	v_mfma_f32_16x16x32_bf16 v[34:37], v[158:161], v[174:177], v[34:37]
	v_mfma_f32_16x16x32_bf16 v[22:25], v[142:145], v[194:197], v[22:25]
	v_mfma_f32_16x16x32_bf16 v[18:21], v[158:161], v[194:197], v[18:21]
	v_mfma_f32_16x16x32_bf16 v[6:9], v[142:145], v[202:205], v[6:9]
	v_mfma_f32_16x16x32_bf16 v[2:5], v[158:161], v[202:205], v[2:5]
	s_setprio 0
	s_barrier
	s_add_i32 s46, 0, 0x18000
	s_add_i32 s47, 0, 0x1c000
	v_add_u32_e32 v78, s46, v243
	v_add_u32_e32 v158, s47, v243
	ds_read_b128 v[58:61], v78
	ds_read_b128 v[62:65], v78 offset:1024
	ds_read_b128 v[74:77], v78 offset:2048
	ds_read_b128 v[78:81], v78 offset:3072
	ds_read_b128 v[130:133], v158
	ds_read_b128 v[142:145], v158 offset:1024
	ds_read_b128 v[154:157], v158 offset:2048
	ds_read_b128 v[158:161], v158 offset:3072
	s_add_u32 s8, s40, 0x158000
	s_addc_u32 s9, s41, 0
	s_mov_b32 m0, s93
	v_lshl_add_u64 v[214:215], s[8:9], 0, v[178:179]
	ds_read_b128 v[162:165], v246 offset:32768
	ds_read_b128 v[166:169], v246 offset:33792
	ds_read_b128 v[170:173], v246 offset:34816
	ds_read_b128 v[174:177], v246 offset:35840
	ds_read_b128 v[184:187], v246 offset:36864
	ds_read_b128 v[194:197], v246 offset:37888
	ds_read_b128 v[198:201], v246 offset:38912
	ds_read_b128 v[202:205], v246 offset:39936
	global_load_lds_dwordx4 v[214:215], off
	v_lshl_add_u64 v[214:215], s[8:9], 0, v[180:181]
	s_mov_b32 m0, s94
	s_nop 0
	global_load_lds_dwordx4 v[214:215], off
	s_waitcnt vmcnt(8)
	s_waitcnt lgkmcnt(0)
	s_barrier
	s_setprio 1
	s_waitcnt lgkmcnt(0)
	v_mfma_f32_16x16x32_bf16 v[150:153], v[58:61], v[162:165], v[150:153]
	v_mfma_f32_16x16x32_bf16 v[146:149], v[74:77], v[162:165], v[146:149]
	v_mfma_f32_16x16x32_bf16 v[126:129], v[58:61], v[170:173], v[126:129]
	v_mfma_f32_16x16x32_bf16 v[122:125], v[74:77], v[170:173], v[122:125]
	v_mfma_f32_16x16x32_bf16 v[110:113], v[58:61], v[184:187], v[110:113]
	v_mfma_f32_16x16x32_bf16 v[106:109], v[74:77], v[184:187], v[106:109]
	v_mfma_f32_16x16x32_bf16 v[94:97], v[58:61], v[198:201], v[94:97]
	v_mfma_f32_16x16x32_bf16 v[90:93], v[74:77], v[198:201], v[90:93]
	v_mfma_f32_16x16x32_bf16 v[150:153], v[62:65], v[166:169], v[150:153]
	v_mfma_f32_16x16x32_bf16 v[146:149], v[78:81], v[166:169], v[146:149]
	v_mfma_f32_16x16x32_bf16 v[126:129], v[62:65], v[174:177], v[126:129]
	v_mfma_f32_16x16x32_bf16 v[122:125], v[78:81], v[174:177], v[122:125]
	v_mfma_f32_16x16x32_bf16 v[110:113], v[62:65], v[194:197], v[110:113]
	v_mfma_f32_16x16x32_bf16 v[106:109], v[78:81], v[194:197], v[106:109]
	v_mfma_f32_16x16x32_bf16 v[94:97], v[62:65], v[202:205], v[94:97]
	v_mfma_f32_16x16x32_bf16 v[90:93], v[78:81], v[202:205], v[90:93]
	s_setprio 0
	s_setprio 1
	v_mfma_f32_16x16x32_bf16 v[138:141], v[130:133], v[162:165], v[138:141]
	v_mfma_f32_16x16x32_bf16 v[134:137], v[154:157], v[162:165], v[134:137]
	v_mfma_f32_16x16x32_bf16 v[118:121], v[130:133], v[170:173], v[118:121]
	v_mfma_f32_16x16x32_bf16 v[114:117], v[154:157], v[170:173], v[114:117]
	v_mfma_f32_16x16x32_bf16 v[102:105], v[130:133], v[184:187], v[102:105]
	v_mfma_f32_16x16x32_bf16 v[98:101], v[154:157], v[184:187], v[98:101]
	v_mfma_f32_16x16x32_bf16 v[86:89], v[130:133], v[198:201], v[86:89]
	v_mfma_f32_16x16x32_bf16 v[82:85], v[154:157], v[198:201], v[82:85]
	v_mfma_f32_16x16x32_bf16 v[138:141], v[142:145], v[166:169], v[138:141]
	v_mfma_f32_16x16x32_bf16 v[134:137], v[158:161], v[166:169], v[134:137]
	v_mfma_f32_16x16x32_bf16 v[118:121], v[142:145], v[174:177], v[118:121]
	v_mfma_f32_16x16x32_bf16 v[114:117], v[158:161], v[174:177], v[114:117]
	v_mfma_f32_16x16x32_bf16 v[102:105], v[142:145], v[194:197], v[102:105]
	v_mfma_f32_16x16x32_bf16 v[98:101], v[158:161], v[194:197], v[98:101]
	v_mfma_f32_16x16x32_bf16 v[86:89], v[142:145], v[202:205], v[86:89]
	v_mfma_f32_16x16x32_bf16 v[82:85], v[158:161], v[202:205], v[82:85]
	s_setprio 0
	s_barrier
; #define PG8_STAGE(bufoff, gbase, voff) do { _Pragma("unroll") for (int _i = 0; _i < 2; ++_i) \
;         __builtin_amdgcn_global_load_lds((const unsigned*)((const char*)(gbase) + (voff)[_i]), (PG8_LAS unsigned*)(lds + (bufoff) + ldsw + _i * 8192), 16, 0, 0); } while (0)
; #define PG8_LDA(dst, b, h) do { _Pragma("unroll") for (int m = 0; m < 4; ++m) _Pragma("unroll") for (int k = 0; k < 2; ++k) dst[m][k] = *(const PG8_LAS bf16x8*)(lds + PG8_SA(b, h) + aoff + m * 2048 + k * 1024); } while (0)
; #define PG8_WAIT_V(n) asm volatile("s_waitcnt vmcnt(" #n ")" ::: "memory")
; #define PG8_WAIT_L(n) asm volatile("s_waitcnt lgkmcnt(" #n ")" ::: "memory")
; #define PG8_BAR __builtin_amdgcn_s_barrier()
; #define PG8_SCHED __builtin_amdgcn_sched_barrier(0)
;     ...
;         for (int t = 0; t < nt * KREP; t += 2) {
;             const bool last = (t == nt * KREP - 2);
;             const int t1w = KREP > 1 ? ((t + 1) & (nt - 1)) : t + 1, t2w = KREP > 1 ? ((t + 2) & (nt - 1)) : t + 2;
;             const char* a1 = cA + (size_t)t1w * kstep;
;             const char* a2 = last ? nA : cA + (size_t)t2w * kstep; const char* b2 = last ? nB : cB + (size_t)t2w * kstep;
;     ...
;             PG8_LDA(At, 1, 1); PG8_STAGE(PG8_SB(1, 0), b3, voffB); PG8_STAGE(PG8_SB(1, 1), b3 + hstep, voffB); PG8_STAGE(PG8_SA(1, 0), a3, voffA);
;             PG8_WAIT_V(8); PG8_WAIT_L(0); PG8_BAR; PG8_MMA(1, 0, At, B0); PG8_MMA(1, 1, At, B1); PG8_BAR; PG8_SCHED;
	s_add_i32 s8, s46, s90
	v_lshl_add_u64 v[206:207], v[206:207], 0, s[28:29]
	s_mov_b32 m0, s8
	ds_read_b128 v[162:165], v246 offset:49152
	ds_read_b128 v[166:169], v246 offset:50176
	ds_read_b128 v[170:173], v246 offset:51200
	ds_read_b128 v[174:177], v246 offset:52224
	ds_read_b128 v[184:187], v246 offset:53248
	ds_read_b128 v[194:197], v246 offset:54272
	ds_read_b128 v[198:201], v246 offset:55296
	ds_read_b128 v[202:205], v246 offset:56320
	global_load_lds_dwordx4 v[206:207], off
	s_add_i32 m0, s8, 0x2000
	s_add_u32 s8, s80, 0x158080
	v_lshl_add_u64 v[206:207], v[208:209], 0, s[28:29]
	s_addc_u32 s9, s81, 0
	s_add_i32 s40, s47, s90
	global_load_lds_dwordx4 v[206:207], off
	v_lshl_add_u64 v[206:207], s[8:9], 0, v[182:183]
	s_mov_b32 m0, s40
	s_nop 0
	global_load_lds_dwordx4 v[206:207], off
	v_lshl_add_u64 v[206:207], s[8:9], 0, v[188:189]
	s_add_i32 m0, s40, 0x2000
	s_nop 0
	global_load_lds_dwordx4 v[206:207], off
	v_lshl_add_u64 v[206:207], v[210:211], 0, s[28:29]
	s_mov_b32 m0, s31
	s_nop 0
	global_load_lds_dwordx4 v[206:207], off
	v_lshl_add_u64 v[206:207], v[212:213], 0, s[28:29]
	s_mov_b32 m0, s56
	s_nop 0
	global_load_lds_dwordx4 v[206:207], off
	s_waitcnt vmcnt(8)
	s_waitcnt lgkmcnt(0)
	s_barrier
	s_setprio 1
	s_waitcnt lgkmcnt(0)
	v_mfma_f32_16x16x32_bf16 v[70:73], v[58:61], v[162:165], v[70:73]
	v_mfma_f32_16x16x32_bf16 v[66:69], v[74:77], v[162:165], v[66:69]
	v_mfma_f32_16x16x32_bf16 v[46:49], v[58:61], v[170:173], v[46:49]
	v_mfma_f32_16x16x32_bf16 v[42:45], v[74:77], v[170:173], v[42:45]
	v_mfma_f32_16x16x32_bf16 v[30:33], v[58:61], v[184:187], v[30:33]
	v_mfma_f32_16x16x32_bf16 v[26:29], v[74:77], v[184:187], v[26:29]
	v_mfma_f32_16x16x32_bf16 v[14:17], v[58:61], v[198:201], v[14:17]
	v_mfma_f32_16x16x32_bf16 v[10:13], v[74:77], v[198:201], v[10:13]
	v_mfma_f32_16x16x32_bf16 v[70:73], v[62:65], v[166:169], v[70:73]
	v_mfma_f32_16x16x32_bf16 v[66:69], v[78:81], v[166:169], v[66:69]
	v_mfma_f32_16x16x32_bf16 v[46:49], v[62:65], v[174:177], v[46:49]
	v_mfma_f32_16x16x32_bf16 v[42:45], v[78:81], v[174:177], v[42:45]
	v_mfma_f32_16x16x32_bf16 v[30:33], v[62:65], v[194:197], v[30:33]
	v_mfma_f32_16x16x32_bf16 v[26:29], v[78:81], v[194:197], v[26:29]
	v_mfma_f32_16x16x32_bf16 v[14:17], v[62:65], v[202:205], v[14:17]
	v_mfma_f32_16x16x32_bf16 v[10:13], v[78:81], v[202:205], v[10:13]
	s_setprio 0
	s_setprio 1
	v_mfma_f32_16x16x32_bf16 v[54:57], v[130:133], v[162:165], v[54:57]
	v_mfma_f32_16x16x32_bf16 v[50:53], v[154:157], v[162:165], v[50:53]
	v_mfma_f32_16x16x32_bf16 v[38:41], v[130:133], v[170:173], v[38:41]
	v_mfma_f32_16x16x32_bf16 v[34:37], v[154:157], v[170:173], v[34:37]
	v_mfma_f32_16x16x32_bf16 v[22:25], v[130:133], v[184:187], v[22:25]
	v_mfma_f32_16x16x32_bf16 v[18:21], v[154:157], v[184:187], v[18:21]
	v_mfma_f32_16x16x32_bf16 v[6:9], v[130:133], v[198:201], v[6:9]
	v_mfma_f32_16x16x32_bf16 v[2:5], v[154:157], v[198:201], v[2:5]
	v_mfma_f32_16x16x32_bf16 v[54:57], v[142:145], v[166:169], v[54:57]
	v_mfma_f32_16x16x32_bf16 v[50:53], v[158:161], v[166:169], v[50:53]
	v_mfma_f32_16x16x32_bf16 v[38:41], v[142:145], v[174:177], v[38:41]
	v_mfma_f32_16x16x32_bf16 v[34:37], v[158:161], v[174:177], v[34:37]
	v_mfma_f32_16x16x32_bf16 v[22:25], v[142:145], v[194:197], v[22:25]
	v_mfma_f32_16x16x32_bf16 v[18:21], v[158:161], v[194:197], v[18:21]
	v_mfma_f32_16x16x32_bf16 v[6:9], v[142:145], v[202:205], v[6:9]
	v_mfma_f32_16x16x32_bf16 v[2:5], v[158:161], v[202:205], v[2:5]
	s_setprio 0
	s_barrier
	s_add_i32 s45, s45, 2
	s_add_u32 s37, s37, 0x100
	s_addc_u32 s44, s44, 0
	s_cmpk_gt_u32 s45, 0x53
	s_mov_b64 s[8:9], s[10:11]
	s_cbranch_scc0 .LBB0_1648
	s_and_b64 vcc, exec, s[76:77]
	s_cbranch_vccz .LBB0_1651
	s_barrier
